# v30 + residual GEMM epilogues with lane-permuted accumulators: 8 rows x 128 B (full cache lines) per memory instruction instead of 16 rows x 64 B, next pair's X loads issued early
# speedup vs baseline: 1.0257x; 1.0156x over previous
;     __device__ __forceinline__ void operator()(const pg8::f32x4 (&acc)[2][2][4][2], const pg8::Unit& u, int wr, int wc, int fr, int fq) const {
;         const int b = u.pm / 9, j = u.pm - b * 9;
;         float* base = (j == 0) ? xc + (size_t)b * CTX * DM : out + ((size_t)b * SEQ + (size_t)(j - 1) * 256) * DM;
;         const float* g = gate + (size_t)((j == 0) ? 16 : b) * MODW;
;         const int col0 = u.pn * 256 + wc * 32 + 4 * fq;
;         pg8::f32x4 gv[2][2];
; #pragma unroll
;         for (int bj = 0; bj < 2; ++bj)
; #pragma unroll
;             for (int n = 0; n < 2; ++n) gv[bj][n] = *(const pg8::f32x4*)(g + col0 + bj * 128 + n * 16);
; #pragma unroll
;         for (int ai = 0; ai < 2; ++ai)
; #pragma unroll
;             for (int m = 0; m < 4; ++m) {
;                 float* rowp = base + (size_t)(ai * 128 + wr * 64 + m * 16 + fr) * DM + col0;
; #pragma unroll
;                 for (int bj = 0; bj < 2; ++bj)
; #pragma unroll
;                     for (int n = 0; n < 2; ++n) {
;                         pg8::f32x4* p = (pg8::f32x4*)(rowp + bj * 128 + n * 16);
;                         pg8::f32x4 xv = *p; xv = xv + gv[bj][n] * acc[ai][bj][m][n]; *p = xv;
;                     }
;                 if (m & 1) asm volatile("" ::: "memory");
;             }
.LBB0_854:
	s_lshl_b64 s[12:13], s[54:55], 2
	v_lshl_or_b32 v88, s62, 8, v171
	s_add_u32 s12, s41, s12
	v_ashrrev_i32_e32 v89, 31, v88
	s_addc_u32 s13, s0, s13
	v_lshlrev_b64 v[168:169], 2, v[88:89]
	v_lshl_add_u64 v[88:89], s[12:13], 0, v[168:169]
	v_lshl_add_u64 v[168:169], s[50:51], 0, v[168:169]
	v_lshl_add_u64 v[178:179], v[168:169], 0, v[148:149]
	global_load_dwordx4 v[108:111], v[88:89], off
	global_load_dwordx4 v[104:107], v[88:89], off offset:64
	global_load_dwordx4 v[100:103], v[88:89], off offset:512
	s_nop 0
	global_load_dwordx4 v[88:91], v[88:89], off offset:576
	s_mov_b64 s[50:51], -1
	s_andn2_b64 vcc, exec, s[38:39]
	s_waitcnt vmcnt(0)
	v_and_b32_e32 v228, 63, v200
	v_lshrrev_b32_e32 v229, 3, v228
	v_and_b32_e32 v184, 3, v228
	v_lshl_or_b32 v184, v184, 4, v229
	v_lshlrev_b32_e32 v184, 2, v184
	v_add_u32_e32 v185, 32, v184
	v_bfe_u32 v229, v228, 2, 1
	v_lshlrev_b32_e32 v186, 6, v229
	v_mov_b32_e32 v187, 0
	v_sub_u32_e32 v188, 0, v229
	ds_bpermute_b32 v228, v184, v108
	ds_bpermute_b32 v229, v184, v104
	s_waitcnt lgkmcnt(0)
	v_bfi_b32 v190, v188, v229, v228
	ds_bpermute_b32 v228, v184, v109
	ds_bpermute_b32 v229, v184, v105
	s_waitcnt lgkmcnt(0)
	v_bfi_b32 v191, v188, v229, v228
	ds_bpermute_b32 v228, v184, v110
	ds_bpermute_b32 v229, v184, v106
	s_waitcnt lgkmcnt(0)
	v_bfi_b32 v192, v188, v229, v228
	ds_bpermute_b32 v228, v184, v111
	ds_bpermute_b32 v229, v184, v107
	s_waitcnt lgkmcnt(0)
	v_bfi_b32 v193, v188, v229, v228
	ds_bpermute_b32 v228, v184, v100
	ds_bpermute_b32 v229, v184, v88
	s_waitcnt lgkmcnt(0)
	v_bfi_b32 v194, v188, v229, v228
	ds_bpermute_b32 v228, v184, v101
	ds_bpermute_b32 v229, v184, v89
	s_waitcnt lgkmcnt(0)
	v_bfi_b32 v195, v188, v229, v228
	ds_bpermute_b32 v228, v184, v102
	ds_bpermute_b32 v229, v184, v90
	s_waitcnt lgkmcnt(0)
	v_bfi_b32 v196, v188, v229, v228
	ds_bpermute_b32 v228, v184, v103
	ds_bpermute_b32 v229, v184, v91
	s_waitcnt lgkmcnt(0)
	v_bfi_b32 v197, v188, v229, v228
	v_lshl_add_u64 v[178:179], v[168:169], 0, v[148:149]
	ds_bpermute_b32 v174, v184, v178
	ds_bpermute_b32 v175, v184, v179
	ds_bpermute_b32 v176, v185, v178
	ds_bpermute_b32 v177, v185, v179
	s_waitcnt lgkmcnt(0)
	v_lshl_add_u64 v[174:175], v[174:175], 0, v[186:187]
	v_lshl_add_u64 v[176:177], v[176:177], 0, v[186:187]
	global_load_dwordx4 v[204:207], v[174:175], off
	global_load_dwordx4 v[208:211], v[176:177], off
	global_load_dwordx4 v[212:215], v[174:175], off offset:512
	global_load_dwordx4 v[216:219], v[176:177], off offset:512
	ds_bpermute_b32 v228, v184, v142
	ds_bpermute_b32 v229, v184, v138
	ds_bpermute_b32 v230, v184, v143
	ds_bpermute_b32 v231, v184, v139
	s_waitcnt lgkmcnt(0)
	v_bfi_b32 v220, v188, v229, v228
	v_bfi_b32 v221, v188, v231, v230
	ds_bpermute_b32 v228, v184, v144
	ds_bpermute_b32 v229, v184, v140
	ds_bpermute_b32 v230, v184, v145
	ds_bpermute_b32 v231, v184, v141
	s_waitcnt lgkmcnt(0)
	v_bfi_b32 v222, v188, v229, v228
	v_bfi_b32 v223, v188, v231, v230
	ds_bpermute_b32 v228, v185, v142
	ds_bpermute_b32 v229, v185, v138
	ds_bpermute_b32 v230, v185, v143
	ds_bpermute_b32 v231, v185, v139
	s_waitcnt lgkmcnt(0)
	v_bfi_b32 v224, v188, v229, v228
	v_bfi_b32 v225, v188, v231, v230
	ds_bpermute_b32 v228, v185, v144
	ds_bpermute_b32 v229, v185, v140
	ds_bpermute_b32 v230, v185, v145
	ds_bpermute_b32 v231, v185, v141
	s_waitcnt lgkmcnt(0)
	v_bfi_b32 v226, v188, v229, v228
	v_bfi_b32 v227, v188, v231, v230
	s_waitcnt vmcnt(2)
	v_pk_fma_f32 v[206:207], v[222:223], v[192:193], v[206:207]
	v_pk_fma_f32 v[204:205], v[220:221], v[190:191], v[204:205]
	v_pk_fma_f32 v[210:211], v[226:227], v[192:193], v[210:211]
	v_pk_fma_f32 v[208:209], v[224:225], v[190:191], v[208:209]
	global_store_dwordx4 v[174:175], v[204:207], off
	global_store_dwordx4 v[176:177], v[208:211], off
	v_lshl_add_u64 v[178:179], v[168:169], 0, v[150:151]
	ds_bpermute_b32 v180, v184, v178
	ds_bpermute_b32 v181, v184, v179
	ds_bpermute_b32 v198, v185, v178
	ds_bpermute_b32 v199, v185, v179
	s_waitcnt lgkmcnt(0)
	v_lshl_add_u64 v[180:181], v[180:181], 0, v[186:187]
	v_lshl_add_u64 v[198:199], v[198:199], 0, v[186:187]
	global_load_dwordx4 v[204:207], v[180:181], off
	global_load_dwordx4 v[208:211], v[198:199], off
	ds_bpermute_b32 v228, v184, v134
	ds_bpermute_b32 v229, v184, v124
	ds_bpermute_b32 v230, v184, v135
	ds_bpermute_b32 v231, v184, v125
	s_waitcnt lgkmcnt(0)
	v_bfi_b32 v220, v188, v229, v228
	v_bfi_b32 v221, v188, v231, v230
	ds_bpermute_b32 v228, v184, v136
	ds_bpermute_b32 v229, v184, v126
	ds_bpermute_b32 v230, v184, v137
	ds_bpermute_b32 v231, v184, v127
	s_waitcnt lgkmcnt(0)
	v_bfi_b32 v222, v188, v229, v228
	v_bfi_b32 v223, v188, v231, v230
	ds_bpermute_b32 v228, v185, v134
	ds_bpermute_b32 v229, v185, v124
	ds_bpermute_b32 v230, v185, v135
	ds_bpermute_b32 v231, v185, v125
	s_waitcnt lgkmcnt(0)
	v_bfi_b32 v224, v188, v229, v228
	v_bfi_b32 v225, v188, v231, v230
	ds_bpermute_b32 v228, v185, v136
	ds_bpermute_b32 v229, v185, v126
	ds_bpermute_b32 v230, v185, v137
	ds_bpermute_b32 v231, v185, v127
	s_waitcnt lgkmcnt(0)
	v_bfi_b32 v226, v188, v229, v228
	v_bfi_b32 v227, v188, v231, v230
	s_waitcnt vmcnt(4)
	v_pk_fma_f32 v[214:215], v[222:223], v[196:197], v[214:215]
	v_pk_fma_f32 v[212:213], v[220:221], v[194:195], v[212:213]
	v_pk_fma_f32 v[218:219], v[226:227], v[196:197], v[218:219]
	v_pk_fma_f32 v[216:217], v[224:225], v[194:195], v[216:217]
	global_store_dwordx4 v[174:175], v[212:215], off offset:512
	global_store_dwordx4 v[176:177], v[216:219], off offset:512
	global_load_dwordx4 v[212:215], v[180:181], off offset:512
	global_load_dwordx4 v[216:219], v[198:199], off offset:512
	ds_bpermute_b32 v228, v184, v130
	ds_bpermute_b32 v229, v184, v120
	ds_bpermute_b32 v230, v184, v131
	ds_bpermute_b32 v231, v184, v121
	s_waitcnt lgkmcnt(0)
;     __device__ __forceinline__ void operator()(const pg8::f32x4 (&acc)[2][2][4][2], const pg8::Unit& u, int wr, int wc, int fr, int fq) const {
;     ...
;         for (int ai = 0; ai < 2; ++ai)
; #pragma unroll
;             for (int m = 0; m < 4; ++m) {
;                 float* rowp = base + (size_t)(ai * 128 + wr * 64 + m * 16 + fr) * DM + col0;
; #pragma unroll
;                 for (int bj = 0; bj < 2; ++bj)
; #pragma unroll
;                     for (int n = 0; n < 2; ++n) {
;                         pg8::f32x4* p = (pg8::f32x4*)(rowp + bj * 128 + n * 16);
;                         pg8::f32x4 xv = *p; xv = xv + gv[bj][n] * acc[ai][bj][m][n]; *p = xv;
;                     }
;                 if (m & 1) asm volatile("" ::: "memory");
;             }
	v_bfi_b32 v220, v188, v229, v228
	v_bfi_b32 v221, v188, v231, v230
	ds_bpermute_b32 v228, v184, v132
	ds_bpermute_b32 v229, v184, v122
	ds_bpermute_b32 v230, v184, v133
	ds_bpermute_b32 v231, v184, v123
	s_waitcnt lgkmcnt(0)
	v_bfi_b32 v222, v188, v229, v228
	v_bfi_b32 v223, v188, v231, v230
	ds_bpermute_b32 v228, v185, v130
	ds_bpermute_b32 v229, v185, v120
	ds_bpermute_b32 v230, v185, v131
	ds_bpermute_b32 v231, v185, v121
	s_waitcnt lgkmcnt(0)
	v_bfi_b32 v224, v188, v229, v228
	v_bfi_b32 v225, v188, v231, v230
	ds_bpermute_b32 v228, v185, v132
	ds_bpermute_b32 v229, v185, v122
	ds_bpermute_b32 v230, v185, v133
	ds_bpermute_b32 v231, v185, v123
	s_waitcnt lgkmcnt(0)
	v_bfi_b32 v226, v188, v229, v228
	v_bfi_b32 v227, v188, v231, v230
	s_waitcnt vmcnt(4)
	v_pk_fma_f32 v[206:207], v[222:223], v[192:193], v[206:207]
	v_pk_fma_f32 v[204:205], v[220:221], v[190:191], v[204:205]
	v_pk_fma_f32 v[210:211], v[226:227], v[192:193], v[210:211]
	v_pk_fma_f32 v[208:209], v[224:225], v[190:191], v[208:209]
	global_store_dwordx4 v[180:181], v[204:207], off
	global_store_dwordx4 v[198:199], v[208:211], off
	v_lshl_add_u64 v[178:179], v[168:169], 0, v[152:153]
	ds_bpermute_b32 v174, v184, v178
	ds_bpermute_b32 v175, v184, v179
	ds_bpermute_b32 v176, v185, v178
	ds_bpermute_b32 v177, v185, v179
	s_waitcnt lgkmcnt(0)
	v_lshl_add_u64 v[174:175], v[174:175], 0, v[186:187]
	v_lshl_add_u64 v[176:177], v[176:177], 0, v[186:187]
	global_load_dwordx4 v[204:207], v[174:175], off
	global_load_dwordx4 v[208:211], v[176:177], off
	ds_bpermute_b32 v228, v184, v116
	ds_bpermute_b32 v229, v184, v112
	ds_bpermute_b32 v230, v184, v117
	ds_bpermute_b32 v231, v184, v113
	s_waitcnt lgkmcnt(0)
	v_bfi_b32 v220, v188, v229, v228
	v_bfi_b32 v221, v188, v231, v230
	ds_bpermute_b32 v228, v184, v118
	ds_bpermute_b32 v229, v184, v114
	ds_bpermute_b32 v230, v184, v119
	ds_bpermute_b32 v231, v184, v115
	s_waitcnt lgkmcnt(0)
	v_bfi_b32 v222, v188, v229, v228
	v_bfi_b32 v223, v188, v231, v230
	ds_bpermute_b32 v228, v185, v116
	ds_bpermute_b32 v229, v185, v112
	ds_bpermute_b32 v230, v185, v117
	ds_bpermute_b32 v231, v185, v113
	s_waitcnt lgkmcnt(0)
	v_bfi_b32 v224, v188, v229, v228
	v_bfi_b32 v225, v188, v231, v230
	ds_bpermute_b32 v228, v185, v118
	ds_bpermute_b32 v229, v185, v114
	ds_bpermute_b32 v230, v185, v119
	ds_bpermute_b32 v231, v185, v115
	s_waitcnt lgkmcnt(0)
	v_bfi_b32 v226, v188, v229, v228
	v_bfi_b32 v227, v188, v231, v230
	s_waitcnt vmcnt(4)
	v_pk_fma_f32 v[214:215], v[222:223], v[196:197], v[214:215]
	v_pk_fma_f32 v[212:213], v[220:221], v[194:195], v[212:213]
	v_pk_fma_f32 v[218:219], v[226:227], v[196:197], v[218:219]
	v_pk_fma_f32 v[216:217], v[224:225], v[194:195], v[216:217]
	global_store_dwordx4 v[180:181], v[212:215], off offset:512
	global_store_dwordx4 v[198:199], v[216:219], off offset:512
	global_load_dwordx4 v[212:215], v[174:175], off offset:512
	global_load_dwordx4 v[216:219], v[176:177], off offset:512
	ds_bpermute_b32 v228, v184, v96
	ds_bpermute_b32 v229, v184, v92
	ds_bpermute_b32 v230, v184, v97
	ds_bpermute_b32 v231, v184, v93
	s_waitcnt lgkmcnt(0)
	v_bfi_b32 v220, v188, v229, v228
	v_bfi_b32 v221, v188, v231, v230
	ds_bpermute_b32 v228, v184, v98
	ds_bpermute_b32 v229, v184, v94
	ds_bpermute_b32 v230, v184, v99
	ds_bpermute_b32 v231, v184, v95
	s_waitcnt lgkmcnt(0)
	v_bfi_b32 v222, v188, v229, v228
	v_bfi_b32 v223, v188, v231, v230
	ds_bpermute_b32 v228, v185, v96
	ds_bpermute_b32 v229, v185, v92
	ds_bpermute_b32 v230, v185, v97
	ds_bpermute_b32 v231, v185, v93
	s_waitcnt lgkmcnt(0)
	v_bfi_b32 v224, v188, v229, v228
	v_bfi_b32 v225, v188, v231, v230
	ds_bpermute_b32 v228, v185, v98
	ds_bpermute_b32 v229, v185, v94
	ds_bpermute_b32 v230, v185, v99
	ds_bpermute_b32 v231, v185, v95
	s_waitcnt lgkmcnt(0)
	v_bfi_b32 v226, v188, v229, v228
	v_bfi_b32 v227, v188, v231, v230
	s_waitcnt vmcnt(4)
	v_pk_fma_f32 v[206:207], v[222:223], v[192:193], v[206:207]
	v_pk_fma_f32 v[204:205], v[220:221], v[190:191], v[204:205]
	v_pk_fma_f32 v[210:211], v[226:227], v[192:193], v[210:211]
	v_pk_fma_f32 v[208:209], v[224:225], v[190:191], v[208:209]
	global_store_dwordx4 v[174:175], v[204:207], off
	global_store_dwordx4 v[176:177], v[208:211], off
	v_lshl_add_u64 v[178:179], v[168:169], 0, v[154:155]
	ds_bpermute_b32 v180, v184, v178
	ds_bpermute_b32 v181, v184, v179
	ds_bpermute_b32 v198, v185, v178
	ds_bpermute_b32 v199, v185, v179
	s_waitcnt lgkmcnt(0)
	v_lshl_add_u64 v[180:181], v[180:181], 0, v[186:187]
	v_lshl_add_u64 v[198:199], v[198:199], 0, v[186:187]
	global_load_dwordx4 v[204:207], v[180:181], off
	global_load_dwordx4 v[208:211], v[198:199], off
	ds_bpermute_b32 v228, v184, v84
	ds_bpermute_b32 v229, v184, v76
	ds_bpermute_b32 v230, v184, v85
	ds_bpermute_b32 v231, v184, v77
	s_waitcnt lgkmcnt(0)
	v_bfi_b32 v220, v188, v229, v228
	v_bfi_b32 v221, v188, v231, v230
	ds_bpermute_b32 v228, v184, v86
	ds_bpermute_b32 v229, v184, v78
	ds_bpermute_b32 v230, v184, v87
	ds_bpermute_b32 v231, v184, v79
	s_waitcnt lgkmcnt(0)
	v_bfi_b32 v222, v188, v229, v228
	v_bfi_b32 v223, v188, v231, v230
	ds_bpermute_b32 v228, v185, v84
	ds_bpermute_b32 v229, v185, v76
	ds_bpermute_b32 v230, v185, v85
	ds_bpermute_b32 v231, v185, v77
	s_waitcnt lgkmcnt(0)
	v_bfi_b32 v224, v188, v229, v228
	v_bfi_b32 v225, v188, v231, v230
	ds_bpermute_b32 v228, v185, v86
	ds_bpermute_b32 v229, v185, v78
	ds_bpermute_b32 v230, v185, v87
	ds_bpermute_b32 v231, v185, v79
	s_waitcnt lgkmcnt(0)
	v_bfi_b32 v226, v188, v229, v228
	v_bfi_b32 v227, v188, v231, v230
	s_waitcnt vmcnt(4)
;     __device__ __forceinline__ void operator()(const pg8::f32x4 (&acc)[2][2][4][2], const pg8::Unit& u, int wr, int wc, int fr, int fq) const {
;     ...
;         for (int ai = 0; ai < 2; ++ai)
; #pragma unroll
;             for (int m = 0; m < 4; ++m) {
;                 float* rowp = base + (size_t)(ai * 128 + wr * 64 + m * 16 + fr) * DM + col0;
; #pragma unroll
;                 for (int bj = 0; bj < 2; ++bj)
; #pragma unroll
;                     for (int n = 0; n < 2; ++n) {
;                         pg8::f32x4* p = (pg8::f32x4*)(rowp + bj * 128 + n * 16);
;                         pg8::f32x4 xv = *p; xv = xv + gv[bj][n] * acc[ai][bj][m][n]; *p = xv;
;                     }
;                 if (m & 1) asm volatile("" ::: "memory");
	v_pk_fma_f32 v[214:215], v[222:223], v[196:197], v[214:215]
	v_pk_fma_f32 v[212:213], v[220:221], v[194:195], v[212:213]
	v_pk_fma_f32 v[218:219], v[226:227], v[196:197], v[218:219]
	v_pk_fma_f32 v[216:217], v[224:225], v[194:195], v[216:217]
	global_store_dwordx4 v[174:175], v[212:215], off offset:512
	global_store_dwordx4 v[176:177], v[216:219], off offset:512
	global_load_dwordx4 v[212:215], v[180:181], off offset:512
	global_load_dwordx4 v[216:219], v[198:199], off offset:512
	ds_bpermute_b32 v228, v184, v80
	ds_bpermute_b32 v229, v184, v72
	ds_bpermute_b32 v230, v184, v81
	ds_bpermute_b32 v231, v184, v73
	s_waitcnt lgkmcnt(0)
	v_bfi_b32 v220, v188, v229, v228
	v_bfi_b32 v221, v188, v231, v230
	ds_bpermute_b32 v228, v184, v82
	ds_bpermute_b32 v229, v184, v74
	ds_bpermute_b32 v230, v184, v83
	ds_bpermute_b32 v231, v184, v75
	s_waitcnt lgkmcnt(0)
	v_bfi_b32 v222, v188, v229, v228
	v_bfi_b32 v223, v188, v231, v230
	ds_bpermute_b32 v228, v185, v80
	ds_bpermute_b32 v229, v185, v72
	ds_bpermute_b32 v230, v185, v81
	ds_bpermute_b32 v231, v185, v73
	s_waitcnt lgkmcnt(0)
	v_bfi_b32 v224, v188, v229, v228
	v_bfi_b32 v225, v188, v231, v230
	ds_bpermute_b32 v228, v185, v82
	ds_bpermute_b32 v229, v185, v74
	ds_bpermute_b32 v230, v185, v83
	ds_bpermute_b32 v231, v185, v75
	s_waitcnt lgkmcnt(0)
	v_bfi_b32 v226, v188, v229, v228
	v_bfi_b32 v227, v188, v231, v230
	s_waitcnt vmcnt(4)
	v_pk_fma_f32 v[206:207], v[222:223], v[192:193], v[206:207]
	v_pk_fma_f32 v[204:205], v[220:221], v[190:191], v[204:205]
	v_pk_fma_f32 v[210:211], v[226:227], v[192:193], v[210:211]
	v_pk_fma_f32 v[208:209], v[224:225], v[190:191], v[208:209]
	global_store_dwordx4 v[180:181], v[204:207], off
	global_store_dwordx4 v[198:199], v[208:211], off
	v_lshl_add_u64 v[178:179], v[168:169], 0, v[156:157]
	ds_bpermute_b32 v174, v184, v178
	ds_bpermute_b32 v175, v184, v179
	ds_bpermute_b32 v176, v185, v178
	ds_bpermute_b32 v177, v185, v179
	s_waitcnt lgkmcnt(0)
	v_lshl_add_u64 v[174:175], v[174:175], 0, v[186:187]
	v_lshl_add_u64 v[176:177], v[176:177], 0, v[186:187]
	global_load_dwordx4 v[204:207], v[174:175], off
	global_load_dwordx4 v[208:211], v[176:177], off
	ds_bpermute_b32 v228, v184, v68
	ds_bpermute_b32 v229, v184, v64
	ds_bpermute_b32 v230, v184, v69
	ds_bpermute_b32 v231, v184, v65
	s_waitcnt lgkmcnt(0)
	v_bfi_b32 v220, v188, v229, v228
	v_bfi_b32 v221, v188, v231, v230
	ds_bpermute_b32 v228, v184, v70
	ds_bpermute_b32 v229, v184, v66
	ds_bpermute_b32 v230, v184, v71
	ds_bpermute_b32 v231, v184, v67
	s_waitcnt lgkmcnt(0)
	v_bfi_b32 v222, v188, v229, v228
	v_bfi_b32 v223, v188, v231, v230
	ds_bpermute_b32 v228, v185, v68
	ds_bpermute_b32 v229, v185, v64
	ds_bpermute_b32 v230, v185, v69
	ds_bpermute_b32 v231, v185, v65
	s_waitcnt lgkmcnt(0)
	v_bfi_b32 v224, v188, v229, v228
	v_bfi_b32 v225, v188, v231, v230
	ds_bpermute_b32 v228, v185, v70
	ds_bpermute_b32 v229, v185, v66
	ds_bpermute_b32 v230, v185, v71
	ds_bpermute_b32 v231, v185, v67
	s_waitcnt lgkmcnt(0)
	v_bfi_b32 v226, v188, v229, v228
	v_bfi_b32 v227, v188, v231, v230
	s_waitcnt vmcnt(4)
	v_pk_fma_f32 v[214:215], v[222:223], v[196:197], v[214:215]
	v_pk_fma_f32 v[212:213], v[220:221], v[194:195], v[212:213]
	v_pk_fma_f32 v[218:219], v[226:227], v[196:197], v[218:219]
	v_pk_fma_f32 v[216:217], v[224:225], v[194:195], v[216:217]
	global_store_dwordx4 v[180:181], v[212:215], off offset:512
	global_store_dwordx4 v[198:199], v[216:219], off offset:512
	global_load_dwordx4 v[212:215], v[174:175], off offset:512
	global_load_dwordx4 v[216:219], v[176:177], off offset:512
	ds_bpermute_b32 v228, v184, v60
	ds_bpermute_b32 v229, v184, v56
	ds_bpermute_b32 v230, v184, v61
	ds_bpermute_b32 v231, v184, v57
	s_waitcnt lgkmcnt(0)
	v_bfi_b32 v220, v188, v229, v228
	v_bfi_b32 v221, v188, v231, v230
	ds_bpermute_b32 v228, v184, v62
	ds_bpermute_b32 v229, v184, v58
	ds_bpermute_b32 v230, v184, v63
	ds_bpermute_b32 v231, v184, v59
	s_waitcnt lgkmcnt(0)
	v_bfi_b32 v222, v188, v229, v228
	v_bfi_b32 v223, v188, v231, v230
	ds_bpermute_b32 v228, v185, v60
	ds_bpermute_b32 v229, v185, v56
	ds_bpermute_b32 v230, v185, v61
	ds_bpermute_b32 v231, v185, v57
	s_waitcnt lgkmcnt(0)
	v_bfi_b32 v224, v188, v229, v228
	v_bfi_b32 v225, v188, v231, v230
	ds_bpermute_b32 v228, v185, v62
	ds_bpermute_b32 v229, v185, v58
	ds_bpermute_b32 v230, v185, v63
	ds_bpermute_b32 v231, v185, v59
	s_waitcnt lgkmcnt(0)
	v_bfi_b32 v226, v188, v229, v228
	v_bfi_b32 v227, v188, v231, v230
	s_waitcnt vmcnt(4)
	v_pk_fma_f32 v[206:207], v[222:223], v[192:193], v[206:207]
	v_pk_fma_f32 v[204:205], v[220:221], v[190:191], v[204:205]
	v_pk_fma_f32 v[210:211], v[226:227], v[192:193], v[210:211]
	v_pk_fma_f32 v[208:209], v[224:225], v[190:191], v[208:209]
	global_store_dwordx4 v[174:175], v[204:207], off
	global_store_dwordx4 v[176:177], v[208:211], off
	v_lshl_add_u64 v[178:179], v[168:169], 0, v[158:159]
	ds_bpermute_b32 v180, v184, v178
	ds_bpermute_b32 v181, v184, v179
	ds_bpermute_b32 v198, v185, v178
	ds_bpermute_b32 v199, v185, v179
	s_waitcnt lgkmcnt(0)
	v_lshl_add_u64 v[180:181], v[180:181], 0, v[186:187]
	v_lshl_add_u64 v[198:199], v[198:199], 0, v[186:187]
	global_load_dwordx4 v[204:207], v[180:181], off
	global_load_dwordx4 v[208:211], v[198:199], off
	ds_bpermute_b32 v228, v184, v52
	ds_bpermute_b32 v229, v184, v44
	ds_bpermute_b32 v230, v184, v53
	ds_bpermute_b32 v231, v184, v45
	s_waitcnt lgkmcnt(0)
	v_bfi_b32 v220, v188, v229, v228
	v_bfi_b32 v221, v188, v231, v230
	ds_bpermute_b32 v228, v184, v54
	ds_bpermute_b32 v229, v184, v46
	ds_bpermute_b32 v230, v184, v55
	ds_bpermute_b32 v231, v184, v47
	s_waitcnt lgkmcnt(0)
;     __device__ __forceinline__ void operator()(const pg8::f32x4 (&acc)[2][2][4][2], const pg8::Unit& u, int wr, int wc, int fr, int fq) const {
;     ...
;         for (int ai = 0; ai < 2; ++ai)
; #pragma unroll
;             for (int m = 0; m < 4; ++m) {
;                 float* rowp = base + (size_t)(ai * 128 + wr * 64 + m * 16 + fr) * DM + col0;
; #pragma unroll
;                 for (int bj = 0; bj < 2; ++bj)
; #pragma unroll
;                     for (int n = 0; n < 2; ++n) {
;                         pg8::f32x4* p = (pg8::f32x4*)(rowp + bj * 128 + n * 16);
;                         pg8::f32x4 xv = *p; xv = xv + gv[bj][n] * acc[ai][bj][m][n]; *p = xv;
;                     }
;                 if (m & 1) asm volatile("" ::: "memory");
	v_bfi_b32 v222, v188, v229, v228
	v_bfi_b32 v223, v188, v231, v230
	ds_bpermute_b32 v228, v185, v52
	ds_bpermute_b32 v229, v185, v44
	ds_bpermute_b32 v230, v185, v53
	ds_bpermute_b32 v231, v185, v45
	s_waitcnt lgkmcnt(0)
	v_bfi_b32 v224, v188, v229, v228
	v_bfi_b32 v225, v188, v231, v230
	ds_bpermute_b32 v228, v185, v54
	ds_bpermute_b32 v229, v185, v46
	ds_bpermute_b32 v230, v185, v55
	ds_bpermute_b32 v231, v185, v47
	s_waitcnt lgkmcnt(0)
	v_bfi_b32 v226, v188, v229, v228
	v_bfi_b32 v227, v188, v231, v230
	s_waitcnt vmcnt(4)
	v_pk_fma_f32 v[214:215], v[222:223], v[196:197], v[214:215]
	v_pk_fma_f32 v[212:213], v[220:221], v[194:195], v[212:213]
	v_pk_fma_f32 v[218:219], v[226:227], v[196:197], v[218:219]
	v_pk_fma_f32 v[216:217], v[224:225], v[194:195], v[216:217]
	global_store_dwordx4 v[174:175], v[212:215], off offset:512
	global_store_dwordx4 v[176:177], v[216:219], off offset:512
	global_load_dwordx4 v[212:215], v[180:181], off offset:512
	global_load_dwordx4 v[216:219], v[198:199], off offset:512
	ds_bpermute_b32 v228, v184, v48
	ds_bpermute_b32 v229, v184, v40
	ds_bpermute_b32 v230, v184, v49
	ds_bpermute_b32 v231, v184, v41
	s_waitcnt lgkmcnt(0)
	v_bfi_b32 v220, v188, v229, v228
	v_bfi_b32 v221, v188, v231, v230
	ds_bpermute_b32 v228, v184, v50
	ds_bpermute_b32 v229, v184, v42
	ds_bpermute_b32 v230, v184, v51
	ds_bpermute_b32 v231, v184, v43
	s_waitcnt lgkmcnt(0)
	v_bfi_b32 v222, v188, v229, v228
	v_bfi_b32 v223, v188, v231, v230
	ds_bpermute_b32 v228, v185, v48
	ds_bpermute_b32 v229, v185, v40
	ds_bpermute_b32 v230, v185, v49
	ds_bpermute_b32 v231, v185, v41
	s_waitcnt lgkmcnt(0)
	v_bfi_b32 v224, v188, v229, v228
	v_bfi_b32 v225, v188, v231, v230
	ds_bpermute_b32 v228, v185, v50
	ds_bpermute_b32 v229, v185, v42
	ds_bpermute_b32 v230, v185, v51
	ds_bpermute_b32 v231, v185, v43
	s_waitcnt lgkmcnt(0)
	v_bfi_b32 v226, v188, v229, v228
	v_bfi_b32 v227, v188, v231, v230
	s_waitcnt vmcnt(4)
	v_pk_fma_f32 v[206:207], v[222:223], v[192:193], v[206:207]
	v_pk_fma_f32 v[204:205], v[220:221], v[190:191], v[204:205]
	v_pk_fma_f32 v[210:211], v[226:227], v[192:193], v[210:211]
	v_pk_fma_f32 v[208:209], v[224:225], v[190:191], v[208:209]
	global_store_dwordx4 v[180:181], v[204:207], off
	global_store_dwordx4 v[198:199], v[208:211], off
	v_lshl_add_u64 v[178:179], v[168:169], 0, v[160:161]
	ds_bpermute_b32 v174, v184, v178
	ds_bpermute_b32 v175, v184, v179
	ds_bpermute_b32 v176, v185, v178
	ds_bpermute_b32 v177, v185, v179
	s_waitcnt lgkmcnt(0)
	v_lshl_add_u64 v[174:175], v[174:175], 0, v[186:187]
	v_lshl_add_u64 v[176:177], v[176:177], 0, v[186:187]
	global_load_dwordx4 v[204:207], v[174:175], off
	global_load_dwordx4 v[208:211], v[176:177], off
	ds_bpermute_b32 v228, v184, v36
	ds_bpermute_b32 v229, v184, v32
	ds_bpermute_b32 v230, v184, v37
	ds_bpermute_b32 v231, v184, v33
	s_waitcnt lgkmcnt(0)
	v_bfi_b32 v220, v188, v229, v228
	v_bfi_b32 v221, v188, v231, v230
	ds_bpermute_b32 v228, v184, v38
	ds_bpermute_b32 v229, v184, v34
	ds_bpermute_b32 v230, v184, v39
	ds_bpermute_b32 v231, v184, v35
	s_waitcnt lgkmcnt(0)
	v_bfi_b32 v222, v188, v229, v228
	v_bfi_b32 v223, v188, v231, v230
	ds_bpermute_b32 v228, v185, v36
	ds_bpermute_b32 v229, v185, v32
	ds_bpermute_b32 v230, v185, v37
	ds_bpermute_b32 v231, v185, v33
	s_waitcnt lgkmcnt(0)
	v_bfi_b32 v224, v188, v229, v228
	v_bfi_b32 v225, v188, v231, v230
	ds_bpermute_b32 v228, v185, v38
	ds_bpermute_b32 v229, v185, v34
	ds_bpermute_b32 v230, v185, v39
	ds_bpermute_b32 v231, v185, v35
	s_waitcnt lgkmcnt(0)
	v_bfi_b32 v226, v188, v229, v228
	v_bfi_b32 v227, v188, v231, v230
	s_waitcnt vmcnt(4)
	v_pk_fma_f32 v[214:215], v[222:223], v[196:197], v[214:215]
	v_pk_fma_f32 v[212:213], v[220:221], v[194:195], v[212:213]
	v_pk_fma_f32 v[218:219], v[226:227], v[196:197], v[218:219]
	v_pk_fma_f32 v[216:217], v[224:225], v[194:195], v[216:217]
	global_store_dwordx4 v[180:181], v[212:215], off offset:512
	global_store_dwordx4 v[198:199], v[216:219], off offset:512
	global_load_dwordx4 v[212:215], v[174:175], off offset:512
	global_load_dwordx4 v[216:219], v[176:177], off offset:512
	ds_bpermute_b32 v228, v184, v28
	ds_bpermute_b32 v229, v184, v24
	ds_bpermute_b32 v230, v184, v29
	ds_bpermute_b32 v231, v184, v25
	s_waitcnt lgkmcnt(0)
	v_bfi_b32 v220, v188, v229, v228
	v_bfi_b32 v221, v188, v231, v230
	ds_bpermute_b32 v228, v184, v30
	ds_bpermute_b32 v229, v184, v26
	ds_bpermute_b32 v230, v184, v31
	ds_bpermute_b32 v231, v184, v27
	s_waitcnt lgkmcnt(0)
	v_bfi_b32 v222, v188, v229, v228
	v_bfi_b32 v223, v188, v231, v230
	ds_bpermute_b32 v228, v185, v28
	ds_bpermute_b32 v229, v185, v24
	ds_bpermute_b32 v230, v185, v29
	ds_bpermute_b32 v231, v185, v25
	s_waitcnt lgkmcnt(0)
	v_bfi_b32 v224, v188, v229, v228
	v_bfi_b32 v225, v188, v231, v230
	ds_bpermute_b32 v228, v185, v30
	ds_bpermute_b32 v229, v185, v26
	ds_bpermute_b32 v230, v185, v31
	ds_bpermute_b32 v231, v185, v27
	s_waitcnt lgkmcnt(0)
;     __device__ __forceinline__ void operator()(const pg8::f32x4 (&acc)[2][2][4][2], const pg8::Unit& u, int wr, int wc, int fr, int fq) const {
;     ...
;         for (int ai = 0; ai < 2; ++ai)
; #pragma unroll
;             for (int m = 0; m < 4; ++m) {
;                 float* rowp = base + (size_t)(ai * 128 + wr * 64 + m * 16 + fr) * DM + col0;
; #pragma unroll
;                 for (int bj = 0; bj < 2; ++bj)
; #pragma unroll
;                     for (int n = 0; n < 2; ++n) {
;                         pg8::f32x4* p = (pg8::f32x4*)(rowp + bj * 128 + n * 16);
;                         pg8::f32x4 xv = *p; xv = xv + gv[bj][n] * acc[ai][bj][m][n]; *p = xv;
;                     }
;                 if (m & 1) asm volatile("" ::: "memory");
	v_bfi_b32 v226, v188, v229, v228
	v_bfi_b32 v227, v188, v231, v230
	s_waitcnt vmcnt(4)
	v_pk_fma_f32 v[206:207], v[222:223], v[192:193], v[206:207]
	v_pk_fma_f32 v[204:205], v[220:221], v[190:191], v[204:205]
	v_pk_fma_f32 v[210:211], v[226:227], v[192:193], v[210:211]
	v_pk_fma_f32 v[208:209], v[224:225], v[190:191], v[208:209]
	global_store_dwordx4 v[174:175], v[204:207], off
	global_store_dwordx4 v[176:177], v[208:211], off
	v_lshl_add_u64 v[178:179], v[168:169], 0, v[162:163]
	ds_bpermute_b32 v180, v184, v178
	ds_bpermute_b32 v181, v184, v179
	ds_bpermute_b32 v198, v185, v178
	ds_bpermute_b32 v199, v185, v179
	s_waitcnt lgkmcnt(0)
	v_lshl_add_u64 v[180:181], v[180:181], 0, v[186:187]
	v_lshl_add_u64 v[198:199], v[198:199], 0, v[186:187]
	global_load_dwordx4 v[204:207], v[180:181], off
	global_load_dwordx4 v[208:211], v[198:199], off
	ds_bpermute_b32 v228, v184, v20
	ds_bpermute_b32 v229, v184, v12
	ds_bpermute_b32 v230, v184, v21
	ds_bpermute_b32 v231, v184, v13
	s_waitcnt lgkmcnt(0)
	v_bfi_b32 v220, v188, v229, v228
	v_bfi_b32 v221, v188, v231, v230
	ds_bpermute_b32 v228, v184, v22
	ds_bpermute_b32 v229, v184, v14
	ds_bpermute_b32 v230, v184, v23
	ds_bpermute_b32 v231, v184, v15
	s_waitcnt lgkmcnt(0)
	v_bfi_b32 v222, v188, v229, v228
	v_bfi_b32 v223, v188, v231, v230
	ds_bpermute_b32 v228, v185, v20
	ds_bpermute_b32 v229, v185, v12
	ds_bpermute_b32 v230, v185, v21
	ds_bpermute_b32 v231, v185, v13
	s_waitcnt lgkmcnt(0)
	v_bfi_b32 v224, v188, v229, v228
	v_bfi_b32 v225, v188, v231, v230
	ds_bpermute_b32 v228, v185, v22
	ds_bpermute_b32 v229, v185, v14
	ds_bpermute_b32 v230, v185, v23
	ds_bpermute_b32 v231, v185, v15
	s_waitcnt lgkmcnt(0)
	v_bfi_b32 v226, v188, v229, v228
	v_bfi_b32 v227, v188, v231, v230
	s_waitcnt vmcnt(4)
	v_pk_fma_f32 v[214:215], v[222:223], v[196:197], v[214:215]
	v_pk_fma_f32 v[212:213], v[220:221], v[194:195], v[212:213]
	v_pk_fma_f32 v[218:219], v[226:227], v[196:197], v[218:219]
	v_pk_fma_f32 v[216:217], v[224:225], v[194:195], v[216:217]
	global_store_dwordx4 v[174:175], v[212:215], off offset:512
	global_store_dwordx4 v[176:177], v[216:219], off offset:512
	global_load_dwordx4 v[212:215], v[180:181], off offset:512
	global_load_dwordx4 v[216:219], v[198:199], off offset:512
	ds_bpermute_b32 v228, v184, v16
	ds_bpermute_b32 v229, v184, v8
	ds_bpermute_b32 v230, v184, v17
	ds_bpermute_b32 v231, v184, v9
	s_waitcnt lgkmcnt(0)
	v_bfi_b32 v220, v188, v229, v228
	v_bfi_b32 v221, v188, v231, v230
	ds_bpermute_b32 v228, v184, v18
	ds_bpermute_b32 v229, v184, v10
	ds_bpermute_b32 v230, v184, v19
	ds_bpermute_b32 v231, v184, v11
	s_waitcnt lgkmcnt(0)
	v_bfi_b32 v222, v188, v229, v228
	v_bfi_b32 v223, v188, v231, v230
	ds_bpermute_b32 v228, v185, v16
	ds_bpermute_b32 v229, v185, v8
	ds_bpermute_b32 v230, v185, v17
	ds_bpermute_b32 v231, v185, v9
	s_waitcnt lgkmcnt(0)
	v_bfi_b32 v224, v188, v229, v228
	v_bfi_b32 v225, v188, v231, v230
	ds_bpermute_b32 v228, v185, v18
	ds_bpermute_b32 v229, v185, v10
	ds_bpermute_b32 v230, v185, v19
	ds_bpermute_b32 v231, v185, v11
	s_waitcnt lgkmcnt(0)
	v_bfi_b32 v226, v188, v229, v228
	v_bfi_b32 v227, v188, v231, v230
	s_waitcnt vmcnt(4)
	v_pk_fma_f32 v[206:207], v[222:223], v[192:193], v[206:207]
	v_pk_fma_f32 v[204:205], v[220:221], v[190:191], v[204:205]
	v_pk_fma_f32 v[210:211], v[226:227], v[192:193], v[210:211]
	v_pk_fma_f32 v[208:209], v[224:225], v[190:191], v[208:209]
	global_store_dwordx4 v[180:181], v[204:207], off
	global_store_dwordx4 v[198:199], v[208:211], off
	ds_bpermute_b32 v228, v184, v4
	ds_bpermute_b32 v229, v184, v0
	ds_bpermute_b32 v230, v184, v5
	ds_bpermute_b32 v231, v184, v1
	s_waitcnt lgkmcnt(0)
	v_bfi_b32 v220, v188, v229, v228
	v_bfi_b32 v221, v188, v231, v230
	ds_bpermute_b32 v228, v184, v6
	ds_bpermute_b32 v229, v184, v2
	ds_bpermute_b32 v230, v184, v7
	ds_bpermute_b32 v231, v184, v3
	s_waitcnt lgkmcnt(0)
	v_bfi_b32 v222, v188, v229, v228
	v_bfi_b32 v223, v188, v231, v230
	ds_bpermute_b32 v228, v185, v4
	ds_bpermute_b32 v229, v185, v0
	ds_bpermute_b32 v230, v185, v5
	ds_bpermute_b32 v231, v185, v1
	s_waitcnt lgkmcnt(0)
	v_bfi_b32 v224, v188, v229, v228
	v_bfi_b32 v225, v188, v231, v230
	ds_bpermute_b32 v228, v185, v6
	ds_bpermute_b32 v229, v185, v2
	ds_bpermute_b32 v230, v185, v7
	ds_bpermute_b32 v231, v185, v3
	s_waitcnt lgkmcnt(0)
	v_bfi_b32 v226, v188, v229, v228
	v_bfi_b32 v227, v188, v231, v230
	s_waitcnt vmcnt(2)
	v_pk_fma_f32 v[214:215], v[222:223], v[196:197], v[214:215]
	v_pk_fma_f32 v[212:213], v[220:221], v[194:195], v[212:213]
	v_pk_fma_f32 v[218:219], v[226:227], v[196:197], v[218:219]
	v_pk_fma_f32 v[216:217], v[224:225], v[194:195], v[216:217]
	global_store_dwordx4 v[180:181], v[212:215], off offset:512
	global_store_dwordx4 v[198:199], v[216:219], off offset:512
	s_cbranch_vccnz .LBB0_844
	s_andn2_b64 vcc, exec, s[10:11]
	s_cbranch_vccnz .LBB0_843
	s_barrier
	s_branch .LBB0_843

;     __device__ __forceinline__ void operator()(const pg8::f32x4 (&acc)[2][2][4][2], const pg8::Unit& u, int wr, int wc, int fr, int fq) const {
;         const int b = u.pm / 9, j = u.pm - b * 9;
;         float* base = (j == 0) ? xc + (size_t)b * CTX * DM : out + ((size_t)b * SEQ + (size_t)(j - 1) * 256) * DM;
;         const float* g = gate + (size_t)((j == 0) ? 16 : b) * MODW;
;         const int col0 = u.pn * 256 + wc * 32 + 4 * fq;
;         pg8::f32x4 gv[2][2];
; #pragma unroll
;         for (int bj = 0; bj < 2; ++bj)
; #pragma unroll
;             for (int n = 0; n < 2; ++n) gv[bj][n] = *(const pg8::f32x4*)(g + col0 + bj * 128 + n * 16);
; #pragma unroll
;         for (int ai = 0; ai < 2; ++ai)
; #pragma unroll
;             for (int m = 0; m < 4; ++m) {
;                 float* rowp = base + (size_t)(ai * 128 + wr * 64 + m * 16 + fr) * DM + col0;
; #pragma unroll
;                 for (int bj = 0; bj < 2; ++bj)
; #pragma unroll
;                     for (int n = 0; n < 2; ++n) {
;                         pg8::f32x4* p = (pg8::f32x4*)(rowp + bj * 128 + n * 16);
;                         pg8::f32x4 xv = *p; xv = xv + gv[bj][n] * acc[ai][bj][m][n]; *p = xv;
;                     }
.LBB0_880:
	s_lshl_b64 s[12:13], s[56:57], 2
	v_lshl_or_b32 v88, s62, 8, v171
	s_add_u32 s12, s41, s12
	v_ashrrev_i32_e32 v89, 31, v88
	s_addc_u32 s13, s0, s13
	v_lshlrev_b64 v[168:169], 2, v[88:89]
	v_lshl_add_u64 v[88:89], s[12:13], 0, v[168:169]
	v_lshl_add_u64 v[168:169], s[52:53], 0, v[168:169]
	v_lshl_add_u64 v[178:179], v[168:169], 0, v[148:149]
	global_load_dwordx4 v[108:111], v[88:89], off
	global_load_dwordx4 v[104:107], v[88:89], off offset:64
	global_load_dwordx4 v[100:103], v[88:89], off offset:512
	s_nop 0
	global_load_dwordx4 v[88:91], v[88:89], off offset:576
	s_mov_b64 s[52:53], -1
	s_andn2_b64 vcc, exec, s[42:43]
	s_waitcnt vmcnt(0)
	v_and_b32_e32 v228, 63, v200
	v_lshrrev_b32_e32 v229, 3, v228
	v_and_b32_e32 v184, 3, v228
	v_lshl_or_b32 v184, v184, 4, v229
	v_lshlrev_b32_e32 v184, 2, v184
	v_add_u32_e32 v185, 32, v184
	v_bfe_u32 v229, v228, 2, 1
	v_lshlrev_b32_e32 v186, 6, v229
	v_mov_b32_e32 v187, 0
	v_sub_u32_e32 v188, 0, v229
	ds_bpermute_b32 v228, v184, v108
	ds_bpermute_b32 v229, v184, v104
	s_waitcnt lgkmcnt(0)
	v_bfi_b32 v190, v188, v229, v228
	ds_bpermute_b32 v228, v184, v109
	ds_bpermute_b32 v229, v184, v105
	s_waitcnt lgkmcnt(0)
	v_bfi_b32 v191, v188, v229, v228
	ds_bpermute_b32 v228, v184, v110
	ds_bpermute_b32 v229, v184, v106
	s_waitcnt lgkmcnt(0)
	v_bfi_b32 v192, v188, v229, v228
	ds_bpermute_b32 v228, v184, v111
	ds_bpermute_b32 v229, v184, v107
	s_waitcnt lgkmcnt(0)
	v_bfi_b32 v193, v188, v229, v228
	ds_bpermute_b32 v228, v184, v100
	ds_bpermute_b32 v229, v184, v88
	s_waitcnt lgkmcnt(0)
	v_bfi_b32 v194, v188, v229, v228
	ds_bpermute_b32 v228, v184, v101
	ds_bpermute_b32 v229, v184, v89
	s_waitcnt lgkmcnt(0)
	v_bfi_b32 v195, v188, v229, v228
	ds_bpermute_b32 v228, v184, v102
	ds_bpermute_b32 v229, v184, v90
	s_waitcnt lgkmcnt(0)
	v_bfi_b32 v196, v188, v229, v228
	ds_bpermute_b32 v228, v184, v103
	ds_bpermute_b32 v229, v184, v91
	s_waitcnt lgkmcnt(0)
	v_bfi_b32 v197, v188, v229, v228
	v_lshl_add_u64 v[178:179], v[168:169], 0, v[148:149]
	ds_bpermute_b32 v174, v184, v178
	ds_bpermute_b32 v175, v184, v179
	ds_bpermute_b32 v176, v185, v178
	ds_bpermute_b32 v177, v185, v179
	s_waitcnt lgkmcnt(0)
	v_lshl_add_u64 v[174:175], v[174:175], 0, v[186:187]
	v_lshl_add_u64 v[176:177], v[176:177], 0, v[186:187]
	global_load_dwordx4 v[204:207], v[174:175], off
	global_load_dwordx4 v[208:211], v[176:177], off
	global_load_dwordx4 v[212:215], v[174:175], off offset:512
	global_load_dwordx4 v[216:219], v[176:177], off offset:512
	ds_bpermute_b32 v228, v184, v142
	ds_bpermute_b32 v229, v184, v138
	ds_bpermute_b32 v230, v184, v143
	ds_bpermute_b32 v231, v184, v139
	s_waitcnt lgkmcnt(0)
	v_bfi_b32 v220, v188, v229, v228
	v_bfi_b32 v221, v188, v231, v230
	ds_bpermute_b32 v228, v184, v144
	ds_bpermute_b32 v229, v184, v140
	ds_bpermute_b32 v230, v184, v145
	ds_bpermute_b32 v231, v184, v141
	s_waitcnt lgkmcnt(0)
	v_bfi_b32 v222, v188, v229, v228
	v_bfi_b32 v223, v188, v231, v230
	ds_bpermute_b32 v228, v185, v142
	ds_bpermute_b32 v229, v185, v138
	ds_bpermute_b32 v230, v185, v143
	ds_bpermute_b32 v231, v185, v139
	s_waitcnt lgkmcnt(0)
	v_bfi_b32 v224, v188, v229, v228
	v_bfi_b32 v225, v188, v231, v230
	ds_bpermute_b32 v228, v185, v144
	ds_bpermute_b32 v229, v185, v140
	ds_bpermute_b32 v230, v185, v145
	ds_bpermute_b32 v231, v185, v141
	s_waitcnt lgkmcnt(0)
	v_bfi_b32 v226, v188, v229, v228
	v_bfi_b32 v227, v188, v231, v230
	s_waitcnt vmcnt(2)
	v_pk_fma_f32 v[206:207], v[222:223], v[192:193], v[206:207]
	v_pk_fma_f32 v[204:205], v[220:221], v[190:191], v[204:205]
	v_pk_fma_f32 v[210:211], v[226:227], v[192:193], v[210:211]
	v_pk_fma_f32 v[208:209], v[224:225], v[190:191], v[208:209]
	global_store_dwordx4 v[174:175], v[204:207], off
	global_store_dwordx4 v[176:177], v[208:211], off
	v_lshl_add_u64 v[178:179], v[168:169], 0, v[150:151]
	ds_bpermute_b32 v180, v184, v178
	ds_bpermute_b32 v181, v184, v179
	ds_bpermute_b32 v198, v185, v178
	ds_bpermute_b32 v199, v185, v179
	s_waitcnt lgkmcnt(0)
	v_lshl_add_u64 v[180:181], v[180:181], 0, v[186:187]
	v_lshl_add_u64 v[198:199], v[198:199], 0, v[186:187]
	global_load_dwordx4 v[204:207], v[180:181], off
	global_load_dwordx4 v[208:211], v[198:199], off
	ds_bpermute_b32 v228, v184, v134
	ds_bpermute_b32 v229, v184, v124
	ds_bpermute_b32 v230, v184, v135
	ds_bpermute_b32 v231, v184, v125
	s_waitcnt lgkmcnt(0)
	v_bfi_b32 v220, v188, v229, v228
	v_bfi_b32 v221, v188, v231, v230
	ds_bpermute_b32 v228, v184, v136
	ds_bpermute_b32 v229, v184, v126
	ds_bpermute_b32 v230, v184, v137
	ds_bpermute_b32 v231, v184, v127
	s_waitcnt lgkmcnt(0)
	v_bfi_b32 v222, v188, v229, v228
	v_bfi_b32 v223, v188, v231, v230
	ds_bpermute_b32 v228, v185, v134
	ds_bpermute_b32 v229, v185, v124
	ds_bpermute_b32 v230, v185, v135
	ds_bpermute_b32 v231, v185, v125
	s_waitcnt lgkmcnt(0)
	v_bfi_b32 v224, v188, v229, v228
	v_bfi_b32 v225, v188, v231, v230
	ds_bpermute_b32 v228, v185, v136
	ds_bpermute_b32 v229, v185, v126
	ds_bpermute_b32 v230, v185, v137
	ds_bpermute_b32 v231, v185, v127
	s_waitcnt lgkmcnt(0)
	v_bfi_b32 v226, v188, v229, v228
	v_bfi_b32 v227, v188, v231, v230
	s_waitcnt vmcnt(4)
	v_pk_fma_f32 v[214:215], v[222:223], v[196:197], v[214:215]
	v_pk_fma_f32 v[212:213], v[220:221], v[194:195], v[212:213]
	v_pk_fma_f32 v[218:219], v[226:227], v[196:197], v[218:219]
	v_pk_fma_f32 v[216:217], v[224:225], v[194:195], v[216:217]
	global_store_dwordx4 v[174:175], v[212:215], off offset:512
	global_store_dwordx4 v[176:177], v[216:219], off offset:512
	global_load_dwordx4 v[212:215], v[180:181], off offset:512
	global_load_dwordx4 v[216:219], v[198:199], off offset:512
	ds_bpermute_b32 v228, v184, v130
	ds_bpermute_b32 v229, v184, v120
	ds_bpermute_b32 v230, v184, v131
	ds_bpermute_b32 v231, v184, v121
	s_waitcnt lgkmcnt(0)
;     __device__ __forceinline__ void operator()(const pg8::f32x4 (&acc)[2][2][4][2], const pg8::Unit& u, int wr, int wc, int fr, int fq) const {
;     ...
;         for (int ai = 0; ai < 2; ++ai)
; #pragma unroll
;             for (int m = 0; m < 4; ++m) {
;                 float* rowp = base + (size_t)(ai * 128 + wr * 64 + m * 16 + fr) * DM + col0;
; #pragma unroll
;                 for (int bj = 0; bj < 2; ++bj)
; #pragma unroll
;                     for (int n = 0; n < 2; ++n) {
;                         pg8::f32x4* p = (pg8::f32x4*)(rowp + bj * 128 + n * 16);
;                         pg8::f32x4 xv = *p; xv = xv + gv[bj][n] * acc[ai][bj][m][n]; *p = xv;
;                     }
;                 if (m & 1) asm volatile("" ::: "memory");
	v_bfi_b32 v220, v188, v229, v228
	v_bfi_b32 v221, v188, v231, v230
	ds_bpermute_b32 v228, v184, v132
	ds_bpermute_b32 v229, v184, v122
	ds_bpermute_b32 v230, v184, v133
	ds_bpermute_b32 v231, v184, v123
	s_waitcnt lgkmcnt(0)
	v_bfi_b32 v222, v188, v229, v228
	v_bfi_b32 v223, v188, v231, v230
	ds_bpermute_b32 v228, v185, v130
	ds_bpermute_b32 v229, v185, v120
	ds_bpermute_b32 v230, v185, v131
	ds_bpermute_b32 v231, v185, v121
	s_waitcnt lgkmcnt(0)
	v_bfi_b32 v224, v188, v229, v228
	v_bfi_b32 v225, v188, v231, v230
	ds_bpermute_b32 v228, v185, v132
	ds_bpermute_b32 v229, v185, v122
	ds_bpermute_b32 v230, v185, v133
	ds_bpermute_b32 v231, v185, v123
	s_waitcnt lgkmcnt(0)
	v_bfi_b32 v226, v188, v229, v228
	v_bfi_b32 v227, v188, v231, v230
	s_waitcnt vmcnt(4)
	v_pk_fma_f32 v[206:207], v[222:223], v[192:193], v[206:207]
	v_pk_fma_f32 v[204:205], v[220:221], v[190:191], v[204:205]
	v_pk_fma_f32 v[210:211], v[226:227], v[192:193], v[210:211]
	v_pk_fma_f32 v[208:209], v[224:225], v[190:191], v[208:209]
	global_store_dwordx4 v[180:181], v[204:207], off
	global_store_dwordx4 v[198:199], v[208:211], off
	v_lshl_add_u64 v[178:179], v[168:169], 0, v[152:153]
	ds_bpermute_b32 v174, v184, v178
	ds_bpermute_b32 v175, v184, v179
	ds_bpermute_b32 v176, v185, v178
	ds_bpermute_b32 v177, v185, v179
	s_waitcnt lgkmcnt(0)
	v_lshl_add_u64 v[174:175], v[174:175], 0, v[186:187]
	v_lshl_add_u64 v[176:177], v[176:177], 0, v[186:187]
	global_load_dwordx4 v[204:207], v[174:175], off
	global_load_dwordx4 v[208:211], v[176:177], off
	ds_bpermute_b32 v228, v184, v116
	ds_bpermute_b32 v229, v184, v112
	ds_bpermute_b32 v230, v184, v117
	ds_bpermute_b32 v231, v184, v113
	s_waitcnt lgkmcnt(0)
	v_bfi_b32 v220, v188, v229, v228
	v_bfi_b32 v221, v188, v231, v230
	ds_bpermute_b32 v228, v184, v118
	ds_bpermute_b32 v229, v184, v114
	ds_bpermute_b32 v230, v184, v119
	ds_bpermute_b32 v231, v184, v115
	s_waitcnt lgkmcnt(0)
	v_bfi_b32 v222, v188, v229, v228
	v_bfi_b32 v223, v188, v231, v230
	ds_bpermute_b32 v228, v185, v116
	ds_bpermute_b32 v229, v185, v112
	ds_bpermute_b32 v230, v185, v117
	ds_bpermute_b32 v231, v185, v113
	s_waitcnt lgkmcnt(0)
	v_bfi_b32 v224, v188, v229, v228
	v_bfi_b32 v225, v188, v231, v230
	ds_bpermute_b32 v228, v185, v118
	ds_bpermute_b32 v229, v185, v114
	ds_bpermute_b32 v230, v185, v119
	ds_bpermute_b32 v231, v185, v115
	s_waitcnt lgkmcnt(0)
	v_bfi_b32 v226, v188, v229, v228
	v_bfi_b32 v227, v188, v231, v230
	s_waitcnt vmcnt(4)
	v_pk_fma_f32 v[214:215], v[222:223], v[196:197], v[214:215]
	v_pk_fma_f32 v[212:213], v[220:221], v[194:195], v[212:213]
	v_pk_fma_f32 v[218:219], v[226:227], v[196:197], v[218:219]
	v_pk_fma_f32 v[216:217], v[224:225], v[194:195], v[216:217]
	global_store_dwordx4 v[180:181], v[212:215], off offset:512
	global_store_dwordx4 v[198:199], v[216:219], off offset:512
	global_load_dwordx4 v[212:215], v[174:175], off offset:512
	global_load_dwordx4 v[216:219], v[176:177], off offset:512
	ds_bpermute_b32 v228, v184, v96
	ds_bpermute_b32 v229, v184, v92
	ds_bpermute_b32 v230, v184, v97
	ds_bpermute_b32 v231, v184, v93
	s_waitcnt lgkmcnt(0)
	v_bfi_b32 v220, v188, v229, v228
	v_bfi_b32 v221, v188, v231, v230
	ds_bpermute_b32 v228, v184, v98
	ds_bpermute_b32 v229, v184, v94
	ds_bpermute_b32 v230, v184, v99
	ds_bpermute_b32 v231, v184, v95
	s_waitcnt lgkmcnt(0)
	v_bfi_b32 v222, v188, v229, v228
	v_bfi_b32 v223, v188, v231, v230
	ds_bpermute_b32 v228, v185, v96
	ds_bpermute_b32 v229, v185, v92
	ds_bpermute_b32 v230, v185, v97
	ds_bpermute_b32 v231, v185, v93
	s_waitcnt lgkmcnt(0)
	v_bfi_b32 v224, v188, v229, v228
	v_bfi_b32 v225, v188, v231, v230
	ds_bpermute_b32 v228, v185, v98
	ds_bpermute_b32 v229, v185, v94
	ds_bpermute_b32 v230, v185, v99
	ds_bpermute_b32 v231, v185, v95
	s_waitcnt lgkmcnt(0)
	v_bfi_b32 v226, v188, v229, v228
	v_bfi_b32 v227, v188, v231, v230
	s_waitcnt vmcnt(4)
	v_pk_fma_f32 v[206:207], v[222:223], v[192:193], v[206:207]
	v_pk_fma_f32 v[204:205], v[220:221], v[190:191], v[204:205]
	v_pk_fma_f32 v[210:211], v[226:227], v[192:193], v[210:211]
	v_pk_fma_f32 v[208:209], v[224:225], v[190:191], v[208:209]
	global_store_dwordx4 v[174:175], v[204:207], off
	global_store_dwordx4 v[176:177], v[208:211], off
	v_lshl_add_u64 v[178:179], v[168:169], 0, v[154:155]
	ds_bpermute_b32 v180, v184, v178
	ds_bpermute_b32 v181, v184, v179
	ds_bpermute_b32 v198, v185, v178
	ds_bpermute_b32 v199, v185, v179
	s_waitcnt lgkmcnt(0)
	v_lshl_add_u64 v[180:181], v[180:181], 0, v[186:187]
	v_lshl_add_u64 v[198:199], v[198:199], 0, v[186:187]
	global_load_dwordx4 v[204:207], v[180:181], off
	global_load_dwordx4 v[208:211], v[198:199], off
	ds_bpermute_b32 v228, v184, v84
	ds_bpermute_b32 v229, v184, v76
	ds_bpermute_b32 v230, v184, v85
	ds_bpermute_b32 v231, v184, v77
	s_waitcnt lgkmcnt(0)
	v_bfi_b32 v220, v188, v229, v228
	v_bfi_b32 v221, v188, v231, v230
	ds_bpermute_b32 v228, v184, v86
	ds_bpermute_b32 v229, v184, v78
	ds_bpermute_b32 v230, v184, v87
	ds_bpermute_b32 v231, v184, v79
	s_waitcnt lgkmcnt(0)
	v_bfi_b32 v222, v188, v229, v228
	v_bfi_b32 v223, v188, v231, v230
	ds_bpermute_b32 v228, v185, v84
	ds_bpermute_b32 v229, v185, v76
	ds_bpermute_b32 v230, v185, v85
	ds_bpermute_b32 v231, v185, v77
	s_waitcnt lgkmcnt(0)
	v_bfi_b32 v224, v188, v229, v228
	v_bfi_b32 v225, v188, v231, v230
	ds_bpermute_b32 v228, v185, v86
	ds_bpermute_b32 v229, v185, v78
	ds_bpermute_b32 v230, v185, v87
	ds_bpermute_b32 v231, v185, v79
	s_waitcnt lgkmcnt(0)
	v_bfi_b32 v226, v188, v229, v228
	v_bfi_b32 v227, v188, v231, v230
	s_waitcnt vmcnt(4)
;     __device__ __forceinline__ void operator()(const pg8::f32x4 (&acc)[2][2][4][2], const pg8::Unit& u, int wr, int wc, int fr, int fq) const {
;     ...
;         for (int ai = 0; ai < 2; ++ai)
; #pragma unroll
;             for (int m = 0; m < 4; ++m) {
;                 float* rowp = base + (size_t)(ai * 128 + wr * 64 + m * 16 + fr) * DM + col0;
; #pragma unroll
;                 for (int bj = 0; bj < 2; ++bj)
; #pragma unroll
;                     for (int n = 0; n < 2; ++n) {
;                         pg8::f32x4* p = (pg8::f32x4*)(rowp + bj * 128 + n * 16);
;                         pg8::f32x4 xv = *p; xv = xv + gv[bj][n] * acc[ai][bj][m][n]; *p = xv;
;                     }
;                 if (m & 1) asm volatile("" ::: "memory");
	v_pk_fma_f32 v[214:215], v[222:223], v[196:197], v[214:215]
	v_pk_fma_f32 v[212:213], v[220:221], v[194:195], v[212:213]
	v_pk_fma_f32 v[218:219], v[226:227], v[196:197], v[218:219]
	v_pk_fma_f32 v[216:217], v[224:225], v[194:195], v[216:217]
	global_store_dwordx4 v[174:175], v[212:215], off offset:512
	global_store_dwordx4 v[176:177], v[216:219], off offset:512
	global_load_dwordx4 v[212:215], v[180:181], off offset:512
	global_load_dwordx4 v[216:219], v[198:199], off offset:512
	ds_bpermute_b32 v228, v184, v80
	ds_bpermute_b32 v229, v184, v72
	ds_bpermute_b32 v230, v184, v81
	ds_bpermute_b32 v231, v184, v73
	s_waitcnt lgkmcnt(0)
	v_bfi_b32 v220, v188, v229, v228
	v_bfi_b32 v221, v188, v231, v230
	ds_bpermute_b32 v228, v184, v82
	ds_bpermute_b32 v229, v184, v74
	ds_bpermute_b32 v230, v184, v83
	ds_bpermute_b32 v231, v184, v75
	s_waitcnt lgkmcnt(0)
	v_bfi_b32 v222, v188, v229, v228
	v_bfi_b32 v223, v188, v231, v230
	ds_bpermute_b32 v228, v185, v80
	ds_bpermute_b32 v229, v185, v72
	ds_bpermute_b32 v230, v185, v81
	ds_bpermute_b32 v231, v185, v73
	s_waitcnt lgkmcnt(0)
	v_bfi_b32 v224, v188, v229, v228
	v_bfi_b32 v225, v188, v231, v230
	ds_bpermute_b32 v228, v185, v82
	ds_bpermute_b32 v229, v185, v74
	ds_bpermute_b32 v230, v185, v83
	ds_bpermute_b32 v231, v185, v75
	s_waitcnt lgkmcnt(0)
	v_bfi_b32 v226, v188, v229, v228
	v_bfi_b32 v227, v188, v231, v230
	s_waitcnt vmcnt(4)
	v_pk_fma_f32 v[206:207], v[222:223], v[192:193], v[206:207]
	v_pk_fma_f32 v[204:205], v[220:221], v[190:191], v[204:205]
	v_pk_fma_f32 v[210:211], v[226:227], v[192:193], v[210:211]
	v_pk_fma_f32 v[208:209], v[224:225], v[190:191], v[208:209]
	global_store_dwordx4 v[180:181], v[204:207], off
	global_store_dwordx4 v[198:199], v[208:211], off
	v_lshl_add_u64 v[178:179], v[168:169], 0, v[156:157]
	ds_bpermute_b32 v174, v184, v178
	ds_bpermute_b32 v175, v184, v179
	ds_bpermute_b32 v176, v185, v178
	ds_bpermute_b32 v177, v185, v179
	s_waitcnt lgkmcnt(0)
	v_lshl_add_u64 v[174:175], v[174:175], 0, v[186:187]
	v_lshl_add_u64 v[176:177], v[176:177], 0, v[186:187]
	global_load_dwordx4 v[204:207], v[174:175], off
	global_load_dwordx4 v[208:211], v[176:177], off
	ds_bpermute_b32 v228, v184, v68
	ds_bpermute_b32 v229, v184, v64
	ds_bpermute_b32 v230, v184, v69
	ds_bpermute_b32 v231, v184, v65
	s_waitcnt lgkmcnt(0)
	v_bfi_b32 v220, v188, v229, v228
	v_bfi_b32 v221, v188, v231, v230
	ds_bpermute_b32 v228, v184, v70
	ds_bpermute_b32 v229, v184, v66
	ds_bpermute_b32 v230, v184, v71
	ds_bpermute_b32 v231, v184, v67
	s_waitcnt lgkmcnt(0)
	v_bfi_b32 v222, v188, v229, v228
	v_bfi_b32 v223, v188, v231, v230
	ds_bpermute_b32 v228, v185, v68
	ds_bpermute_b32 v229, v185, v64
	ds_bpermute_b32 v230, v185, v69
	ds_bpermute_b32 v231, v185, v65
	s_waitcnt lgkmcnt(0)
	v_bfi_b32 v224, v188, v229, v228
	v_bfi_b32 v225, v188, v231, v230
	ds_bpermute_b32 v228, v185, v70
	ds_bpermute_b32 v229, v185, v66
	ds_bpermute_b32 v230, v185, v71
	ds_bpermute_b32 v231, v185, v67
	s_waitcnt lgkmcnt(0)
	v_bfi_b32 v226, v188, v229, v228
	v_bfi_b32 v227, v188, v231, v230
	s_waitcnt vmcnt(4)
	v_pk_fma_f32 v[214:215], v[222:223], v[196:197], v[214:215]
	v_pk_fma_f32 v[212:213], v[220:221], v[194:195], v[212:213]
	v_pk_fma_f32 v[218:219], v[226:227], v[196:197], v[218:219]
	v_pk_fma_f32 v[216:217], v[224:225], v[194:195], v[216:217]
	global_store_dwordx4 v[180:181], v[212:215], off offset:512
	global_store_dwordx4 v[198:199], v[216:219], off offset:512
	global_load_dwordx4 v[212:215], v[174:175], off offset:512
	global_load_dwordx4 v[216:219], v[176:177], off offset:512
	ds_bpermute_b32 v228, v184, v60
	ds_bpermute_b32 v229, v184, v56
	ds_bpermute_b32 v230, v184, v61
	ds_bpermute_b32 v231, v184, v57
	s_waitcnt lgkmcnt(0)
	v_bfi_b32 v220, v188, v229, v228
	v_bfi_b32 v221, v188, v231, v230
	ds_bpermute_b32 v228, v184, v62
	ds_bpermute_b32 v229, v184, v58
	ds_bpermute_b32 v230, v184, v63
	ds_bpermute_b32 v231, v184, v59
	s_waitcnt lgkmcnt(0)
	v_bfi_b32 v222, v188, v229, v228
	v_bfi_b32 v223, v188, v231, v230
	ds_bpermute_b32 v228, v185, v60
	ds_bpermute_b32 v229, v185, v56
	ds_bpermute_b32 v230, v185, v61
	ds_bpermute_b32 v231, v185, v57
	s_waitcnt lgkmcnt(0)
	v_bfi_b32 v224, v188, v229, v228
	v_bfi_b32 v225, v188, v231, v230
	ds_bpermute_b32 v228, v185, v62
	ds_bpermute_b32 v229, v185, v58
	ds_bpermute_b32 v230, v185, v63
	ds_bpermute_b32 v231, v185, v59
	s_waitcnt lgkmcnt(0)
	v_bfi_b32 v226, v188, v229, v228
	v_bfi_b32 v227, v188, v231, v230
	s_waitcnt vmcnt(4)
	v_pk_fma_f32 v[206:207], v[222:223], v[192:193], v[206:207]
	v_pk_fma_f32 v[204:205], v[220:221], v[190:191], v[204:205]
	v_pk_fma_f32 v[210:211], v[226:227], v[192:193], v[210:211]
	v_pk_fma_f32 v[208:209], v[224:225], v[190:191], v[208:209]
	global_store_dwordx4 v[174:175], v[204:207], off
	global_store_dwordx4 v[176:177], v[208:211], off
	v_lshl_add_u64 v[178:179], v[168:169], 0, v[158:159]
	ds_bpermute_b32 v180, v184, v178
	ds_bpermute_b32 v181, v184, v179
	ds_bpermute_b32 v198, v185, v178
	ds_bpermute_b32 v199, v185, v179
	s_waitcnt lgkmcnt(0)
	v_lshl_add_u64 v[180:181], v[180:181], 0, v[186:187]
	v_lshl_add_u64 v[198:199], v[198:199], 0, v[186:187]
	global_load_dwordx4 v[204:207], v[180:181], off
	global_load_dwordx4 v[208:211], v[198:199], off
	ds_bpermute_b32 v228, v184, v52
	ds_bpermute_b32 v229, v184, v44
	ds_bpermute_b32 v230, v184, v53
	ds_bpermute_b32 v231, v184, v45
	s_waitcnt lgkmcnt(0)
	v_bfi_b32 v220, v188, v229, v228
	v_bfi_b32 v221, v188, v231, v230
	ds_bpermute_b32 v228, v184, v54
	ds_bpermute_b32 v229, v184, v46
	ds_bpermute_b32 v230, v184, v55
	ds_bpermute_b32 v231, v184, v47
	s_waitcnt lgkmcnt(0)
;     __device__ __forceinline__ void operator()(const pg8::f32x4 (&acc)[2][2][4][2], const pg8::Unit& u, int wr, int wc, int fr, int fq) const {
;     ...
;         for (int ai = 0; ai < 2; ++ai)
; #pragma unroll
;             for (int m = 0; m < 4; ++m) {
;                 float* rowp = base + (size_t)(ai * 128 + wr * 64 + m * 16 + fr) * DM + col0;
; #pragma unroll
;                 for (int bj = 0; bj < 2; ++bj)
; #pragma unroll
;                     for (int n = 0; n < 2; ++n) {
;                         pg8::f32x4* p = (pg8::f32x4*)(rowp + bj * 128 + n * 16);
;                         pg8::f32x4 xv = *p; xv = xv + gv[bj][n] * acc[ai][bj][m][n]; *p = xv;
;                     }
;                 if (m & 1) asm volatile("" ::: "memory");
	v_bfi_b32 v222, v188, v229, v228
	v_bfi_b32 v223, v188, v231, v230
	ds_bpermute_b32 v228, v185, v52
	ds_bpermute_b32 v229, v185, v44
	ds_bpermute_b32 v230, v185, v53
	ds_bpermute_b32 v231, v185, v45
	s_waitcnt lgkmcnt(0)
	v_bfi_b32 v224, v188, v229, v228
	v_bfi_b32 v225, v188, v231, v230
	ds_bpermute_b32 v228, v185, v54
	ds_bpermute_b32 v229, v185, v46
	ds_bpermute_b32 v230, v185, v55
	ds_bpermute_b32 v231, v185, v47
	s_waitcnt lgkmcnt(0)
	v_bfi_b32 v226, v188, v229, v228
	v_bfi_b32 v227, v188, v231, v230
	s_waitcnt vmcnt(4)
	v_pk_fma_f32 v[214:215], v[222:223], v[196:197], v[214:215]
	v_pk_fma_f32 v[212:213], v[220:221], v[194:195], v[212:213]
	v_pk_fma_f32 v[218:219], v[226:227], v[196:197], v[218:219]
	v_pk_fma_f32 v[216:217], v[224:225], v[194:195], v[216:217]
	global_store_dwordx4 v[174:175], v[212:215], off offset:512
	global_store_dwordx4 v[176:177], v[216:219], off offset:512
	global_load_dwordx4 v[212:215], v[180:181], off offset:512
	global_load_dwordx4 v[216:219], v[198:199], off offset:512
	ds_bpermute_b32 v228, v184, v48
	ds_bpermute_b32 v229, v184, v40
	ds_bpermute_b32 v230, v184, v49
	ds_bpermute_b32 v231, v184, v41
	s_waitcnt lgkmcnt(0)
	v_bfi_b32 v220, v188, v229, v228
	v_bfi_b32 v221, v188, v231, v230
	ds_bpermute_b32 v228, v184, v50
	ds_bpermute_b32 v229, v184, v42
	ds_bpermute_b32 v230, v184, v51
	ds_bpermute_b32 v231, v184, v43
	s_waitcnt lgkmcnt(0)
	v_bfi_b32 v222, v188, v229, v228
	v_bfi_b32 v223, v188, v231, v230
	ds_bpermute_b32 v228, v185, v48
	ds_bpermute_b32 v229, v185, v40
	ds_bpermute_b32 v230, v185, v49
	ds_bpermute_b32 v231, v185, v41
	s_waitcnt lgkmcnt(0)
	v_bfi_b32 v224, v188, v229, v228
	v_bfi_b32 v225, v188, v231, v230
	ds_bpermute_b32 v228, v185, v50
	ds_bpermute_b32 v229, v185, v42
	ds_bpermute_b32 v230, v185, v51
	ds_bpermute_b32 v231, v185, v43
	s_waitcnt lgkmcnt(0)
	v_bfi_b32 v226, v188, v229, v228
	v_bfi_b32 v227, v188, v231, v230
	s_waitcnt vmcnt(4)
	v_pk_fma_f32 v[206:207], v[222:223], v[192:193], v[206:207]
	v_pk_fma_f32 v[204:205], v[220:221], v[190:191], v[204:205]
	v_pk_fma_f32 v[210:211], v[226:227], v[192:193], v[210:211]
	v_pk_fma_f32 v[208:209], v[224:225], v[190:191], v[208:209]
	global_store_dwordx4 v[180:181], v[204:207], off
	global_store_dwordx4 v[198:199], v[208:211], off
	v_lshl_add_u64 v[178:179], v[168:169], 0, v[160:161]
	ds_bpermute_b32 v174, v184, v178
	ds_bpermute_b32 v175, v184, v179
	ds_bpermute_b32 v176, v185, v178
	ds_bpermute_b32 v177, v185, v179
	s_waitcnt lgkmcnt(0)
	v_lshl_add_u64 v[174:175], v[174:175], 0, v[186:187]
	v_lshl_add_u64 v[176:177], v[176:177], 0, v[186:187]
	global_load_dwordx4 v[204:207], v[174:175], off
	global_load_dwordx4 v[208:211], v[176:177], off
	ds_bpermute_b32 v228, v184, v36
	ds_bpermute_b32 v229, v184, v32
	ds_bpermute_b32 v230, v184, v37
	ds_bpermute_b32 v231, v184, v33
	s_waitcnt lgkmcnt(0)
	v_bfi_b32 v220, v188, v229, v228
	v_bfi_b32 v221, v188, v231, v230
	ds_bpermute_b32 v228, v184, v38
	ds_bpermute_b32 v229, v184, v34
	ds_bpermute_b32 v230, v184, v39
	ds_bpermute_b32 v231, v184, v35
	s_waitcnt lgkmcnt(0)
	v_bfi_b32 v222, v188, v229, v228
	v_bfi_b32 v223, v188, v231, v230
	ds_bpermute_b32 v228, v185, v36
	ds_bpermute_b32 v229, v185, v32
	ds_bpermute_b32 v230, v185, v37
	ds_bpermute_b32 v231, v185, v33
	s_waitcnt lgkmcnt(0)
	v_bfi_b32 v224, v188, v229, v228
	v_bfi_b32 v225, v188, v231, v230
	ds_bpermute_b32 v228, v185, v38
	ds_bpermute_b32 v229, v185, v34
	ds_bpermute_b32 v230, v185, v39
	ds_bpermute_b32 v231, v185, v35
	s_waitcnt lgkmcnt(0)
	v_bfi_b32 v226, v188, v229, v228
	v_bfi_b32 v227, v188, v231, v230
	s_waitcnt vmcnt(4)
	v_pk_fma_f32 v[214:215], v[222:223], v[196:197], v[214:215]
	v_pk_fma_f32 v[212:213], v[220:221], v[194:195], v[212:213]
	v_pk_fma_f32 v[218:219], v[226:227], v[196:197], v[218:219]
	v_pk_fma_f32 v[216:217], v[224:225], v[194:195], v[216:217]
	global_store_dwordx4 v[180:181], v[212:215], off offset:512
	global_store_dwordx4 v[198:199], v[216:219], off offset:512
	global_load_dwordx4 v[212:215], v[174:175], off offset:512
	global_load_dwordx4 v[216:219], v[176:177], off offset:512
	ds_bpermute_b32 v228, v184, v28
	ds_bpermute_b32 v229, v184, v24
	ds_bpermute_b32 v230, v184, v29
	ds_bpermute_b32 v231, v184, v25
	s_waitcnt lgkmcnt(0)
	v_bfi_b32 v220, v188, v229, v228
	v_bfi_b32 v221, v188, v231, v230
	ds_bpermute_b32 v228, v184, v30
	ds_bpermute_b32 v229, v184, v26
	ds_bpermute_b32 v230, v184, v31
	ds_bpermute_b32 v231, v184, v27
	s_waitcnt lgkmcnt(0)
	v_bfi_b32 v222, v188, v229, v228
	v_bfi_b32 v223, v188, v231, v230
	ds_bpermute_b32 v228, v185, v28
	ds_bpermute_b32 v229, v185, v24
	ds_bpermute_b32 v230, v185, v29
	ds_bpermute_b32 v231, v185, v25
	s_waitcnt lgkmcnt(0)
	v_bfi_b32 v224, v188, v229, v228
	v_bfi_b32 v225, v188, v231, v230
	ds_bpermute_b32 v228, v185, v30
	ds_bpermute_b32 v229, v185, v26
	ds_bpermute_b32 v230, v185, v31
	ds_bpermute_b32 v231, v185, v27
	s_waitcnt lgkmcnt(0)
;     __device__ __forceinline__ void operator()(const pg8::f32x4 (&acc)[2][2][4][2], const pg8::Unit& u, int wr, int wc, int fr, int fq) const {
;     ...
;         for (int ai = 0; ai < 2; ++ai)
; #pragma unroll
;             for (int m = 0; m < 4; ++m) {
;                 float* rowp = base + (size_t)(ai * 128 + wr * 64 + m * 16 + fr) * DM + col0;
; #pragma unroll
;                 for (int bj = 0; bj < 2; ++bj)
; #pragma unroll
;                     for (int n = 0; n < 2; ++n) {
;                         pg8::f32x4* p = (pg8::f32x4*)(rowp + bj * 128 + n * 16);
;                         pg8::f32x4 xv = *p; xv = xv + gv[bj][n] * acc[ai][bj][m][n]; *p = xv;
;                     }
;                 if (m & 1) asm volatile("" ::: "memory");
	v_bfi_b32 v226, v188, v229, v228
	v_bfi_b32 v227, v188, v231, v230
	s_waitcnt vmcnt(4)
	v_pk_fma_f32 v[206:207], v[222:223], v[192:193], v[206:207]
	v_pk_fma_f32 v[204:205], v[220:221], v[190:191], v[204:205]
	v_pk_fma_f32 v[210:211], v[226:227], v[192:193], v[210:211]
	v_pk_fma_f32 v[208:209], v[224:225], v[190:191], v[208:209]
	global_store_dwordx4 v[174:175], v[204:207], off
	global_store_dwordx4 v[176:177], v[208:211], off
	v_lshl_add_u64 v[178:179], v[168:169], 0, v[162:163]
	ds_bpermute_b32 v180, v184, v178
	ds_bpermute_b32 v181, v184, v179
	ds_bpermute_b32 v198, v185, v178
	ds_bpermute_b32 v199, v185, v179
	s_waitcnt lgkmcnt(0)
	v_lshl_add_u64 v[180:181], v[180:181], 0, v[186:187]
	v_lshl_add_u64 v[198:199], v[198:199], 0, v[186:187]
	global_load_dwordx4 v[204:207], v[180:181], off
	global_load_dwordx4 v[208:211], v[198:199], off
	ds_bpermute_b32 v228, v184, v20
	ds_bpermute_b32 v229, v184, v12
	ds_bpermute_b32 v230, v184, v21
	ds_bpermute_b32 v231, v184, v13
	s_waitcnt lgkmcnt(0)
	v_bfi_b32 v220, v188, v229, v228
	v_bfi_b32 v221, v188, v231, v230
	ds_bpermute_b32 v228, v184, v22
	ds_bpermute_b32 v229, v184, v14
	ds_bpermute_b32 v230, v184, v23
	ds_bpermute_b32 v231, v184, v15
	s_waitcnt lgkmcnt(0)
	v_bfi_b32 v222, v188, v229, v228
	v_bfi_b32 v223, v188, v231, v230
	ds_bpermute_b32 v228, v185, v20
	ds_bpermute_b32 v229, v185, v12
	ds_bpermute_b32 v230, v185, v21
	ds_bpermute_b32 v231, v185, v13
	s_waitcnt lgkmcnt(0)
	v_bfi_b32 v224, v188, v229, v228
	v_bfi_b32 v225, v188, v231, v230
	ds_bpermute_b32 v228, v185, v22
	ds_bpermute_b32 v229, v185, v14
	ds_bpermute_b32 v230, v185, v23
	ds_bpermute_b32 v231, v185, v15
	s_waitcnt lgkmcnt(0)
	v_bfi_b32 v226, v188, v229, v228
	v_bfi_b32 v227, v188, v231, v230
	s_waitcnt vmcnt(4)
	v_pk_fma_f32 v[214:215], v[222:223], v[196:197], v[214:215]
	v_pk_fma_f32 v[212:213], v[220:221], v[194:195], v[212:213]
	v_pk_fma_f32 v[218:219], v[226:227], v[196:197], v[218:219]
	v_pk_fma_f32 v[216:217], v[224:225], v[194:195], v[216:217]
	global_store_dwordx4 v[174:175], v[212:215], off offset:512
	global_store_dwordx4 v[176:177], v[216:219], off offset:512
	global_load_dwordx4 v[212:215], v[180:181], off offset:512
	global_load_dwordx4 v[216:219], v[198:199], off offset:512
	ds_bpermute_b32 v228, v184, v16
	ds_bpermute_b32 v229, v184, v8
	ds_bpermute_b32 v230, v184, v17
	ds_bpermute_b32 v231, v184, v9
	s_waitcnt lgkmcnt(0)
	v_bfi_b32 v220, v188, v229, v228
	v_bfi_b32 v221, v188, v231, v230
	ds_bpermute_b32 v228, v184, v18
	ds_bpermute_b32 v229, v184, v10
	ds_bpermute_b32 v230, v184, v19
	ds_bpermute_b32 v231, v184, v11
	s_waitcnt lgkmcnt(0)
	v_bfi_b32 v222, v188, v229, v228
	v_bfi_b32 v223, v188, v231, v230
	ds_bpermute_b32 v228, v185, v16
	ds_bpermute_b32 v229, v185, v8
	ds_bpermute_b32 v230, v185, v17
	ds_bpermute_b32 v231, v185, v9
	s_waitcnt lgkmcnt(0)
	v_bfi_b32 v224, v188, v229, v228
	v_bfi_b32 v225, v188, v231, v230
	ds_bpermute_b32 v228, v185, v18
	ds_bpermute_b32 v229, v185, v10
	ds_bpermute_b32 v230, v185, v19
	ds_bpermute_b32 v231, v185, v11
	s_waitcnt lgkmcnt(0)
	v_bfi_b32 v226, v188, v229, v228
	v_bfi_b32 v227, v188, v231, v230
	s_waitcnt vmcnt(4)
	v_pk_fma_f32 v[206:207], v[222:223], v[192:193], v[206:207]
	v_pk_fma_f32 v[204:205], v[220:221], v[190:191], v[204:205]
	v_pk_fma_f32 v[210:211], v[226:227], v[192:193], v[210:211]
	v_pk_fma_f32 v[208:209], v[224:225], v[190:191], v[208:209]
	global_store_dwordx4 v[180:181], v[204:207], off
	global_store_dwordx4 v[198:199], v[208:211], off
	ds_bpermute_b32 v228, v184, v4
	ds_bpermute_b32 v229, v184, v0
	ds_bpermute_b32 v230, v184, v5
	ds_bpermute_b32 v231, v184, v1
	s_waitcnt lgkmcnt(0)
	v_bfi_b32 v220, v188, v229, v228
	v_bfi_b32 v221, v188, v231, v230
	ds_bpermute_b32 v228, v184, v6
	ds_bpermute_b32 v229, v184, v2
	ds_bpermute_b32 v230, v184, v7
	ds_bpermute_b32 v231, v184, v3
	s_waitcnt lgkmcnt(0)
	v_bfi_b32 v222, v188, v229, v228
	v_bfi_b32 v223, v188, v231, v230
	ds_bpermute_b32 v228, v185, v4
	ds_bpermute_b32 v229, v185, v0
	ds_bpermute_b32 v230, v185, v5
	ds_bpermute_b32 v231, v185, v1
	s_waitcnt lgkmcnt(0)
	v_bfi_b32 v224, v188, v229, v228
	v_bfi_b32 v225, v188, v231, v230
	ds_bpermute_b32 v228, v185, v6
	ds_bpermute_b32 v229, v185, v2
	ds_bpermute_b32 v230, v185, v7
	ds_bpermute_b32 v231, v185, v3
	s_waitcnt lgkmcnt(0)
	v_bfi_b32 v226, v188, v229, v228
	v_bfi_b32 v227, v188, v231, v230
	s_waitcnt vmcnt(2)
	v_pk_fma_f32 v[214:215], v[222:223], v[196:197], v[214:215]
	v_pk_fma_f32 v[212:213], v[220:221], v[194:195], v[212:213]
	v_pk_fma_f32 v[218:219], v[226:227], v[196:197], v[218:219]
	v_pk_fma_f32 v[216:217], v[224:225], v[194:195], v[216:217]
	global_store_dwordx4 v[180:181], v[212:215], off offset:512
	global_store_dwordx4 v[198:199], v[216:219], off offset:512
	s_cbranch_vccnz .LBB0_866
	s_andn2_b64 vcc, exec, s[10:11]
	s_cbranch_vccnz .LBB0_865
	s_barrier
	s_branch .LBB0_865

;     __device__ __forceinline__ void operator()(const pg8::f32x4 (&acc)[2][2][4][2], const pg8::Unit& u, int wr, int wc, int fr, int fq) const {
;         const int b = u.pm / 9, j = u.pm - b * 9;
;         float* base = (j == 0) ? xc + (size_t)b * CTX * DM : out + ((size_t)b * SEQ + (size_t)(j - 1) * 256) * DM;
;         const float* g = gate + (size_t)((j == 0) ? 16 : b) * MODW;
;         const int col0 = u.pn * 256 + wc * 32 + 4 * fq;
;         pg8::f32x4 gv[2][2];
; #pragma unroll
;         for (int bj = 0; bj < 2; ++bj)
; #pragma unroll
;             for (int n = 0; n < 2; ++n) gv[bj][n] = *(const pg8::f32x4*)(g + col0 + bj * 128 + n * 16);
; #pragma unroll
;         for (int ai = 0; ai < 2; ++ai)
; #pragma unroll
;             for (int m = 0; m < 4; ++m) {
;                 float* rowp = base + (size_t)(ai * 128 + wr * 64 + m * 16 + fr) * DM + col0;
; #pragma unroll
;                 for (int bj = 0; bj < 2; ++bj)
; #pragma unroll
;                     for (int n = 0; n < 2; ++n) {
;                         pg8::f32x4* p = (pg8::f32x4*)(rowp + bj * 128 + n * 16);
;                         pg8::f32x4 xv = *p; xv = xv + gv[bj][n] * acc[ai][bj][m][n]; *p = xv;
;                     }
.LBB0_1099:
	s_lshl_b64 s[12:13], s[58:59], 2
	v_lshl_or_b32 v88, s62, 8, v171
	s_add_u32 s12, s11, s12
	v_ashrrev_i32_e32 v89, 31, v88
	s_addc_u32 s13, s24, s13
	v_lshlrev_b64 v[168:169], 2, v[88:89]
	v_lshl_add_u64 v[88:89], s[12:13], 0, v[168:169]
	v_lshl_add_u64 v[168:169], s[50:51], 0, v[168:169]
	v_lshl_add_u64 v[178:179], v[168:169], 0, v[148:149]
	global_load_dwordx4 v[108:111], v[88:89], off
	global_load_dwordx4 v[104:107], v[88:89], off offset:64
	global_load_dwordx4 v[100:103], v[88:89], off offset:512
	s_nop 0
	global_load_dwordx4 v[88:91], v[88:89], off offset:576
	s_mov_b64 s[50:51], -1
	s_and_b64 vcc, exec, s[40:41]
	s_waitcnt vmcnt(0)
	v_and_b32_e32 v228, 63, v200
	v_lshrrev_b32_e32 v229, 3, v228
	v_and_b32_e32 v184, 3, v228
	v_lshl_or_b32 v184, v184, 4, v229
	v_lshlrev_b32_e32 v184, 2, v184
	v_add_u32_e32 v185, 32, v184
	v_bfe_u32 v229, v228, 2, 1
	v_lshlrev_b32_e32 v186, 6, v229
	v_mov_b32_e32 v187, 0
	v_sub_u32_e32 v188, 0, v229
	ds_bpermute_b32 v228, v184, v108
	ds_bpermute_b32 v229, v184, v104
	s_waitcnt lgkmcnt(0)
	v_bfi_b32 v190, v188, v229, v228
	ds_bpermute_b32 v228, v184, v109
	ds_bpermute_b32 v229, v184, v105
	s_waitcnt lgkmcnt(0)
	v_bfi_b32 v191, v188, v229, v228
	ds_bpermute_b32 v228, v184, v110
	ds_bpermute_b32 v229, v184, v106
	s_waitcnt lgkmcnt(0)
	v_bfi_b32 v192, v188, v229, v228
	ds_bpermute_b32 v228, v184, v111
	ds_bpermute_b32 v229, v184, v107
	s_waitcnt lgkmcnt(0)
	v_bfi_b32 v193, v188, v229, v228
	ds_bpermute_b32 v228, v184, v100
	ds_bpermute_b32 v229, v184, v88
	s_waitcnt lgkmcnt(0)
	v_bfi_b32 v194, v188, v229, v228
	ds_bpermute_b32 v228, v184, v101
	ds_bpermute_b32 v229, v184, v89
	s_waitcnt lgkmcnt(0)
	v_bfi_b32 v195, v188, v229, v228
	ds_bpermute_b32 v228, v184, v102
	ds_bpermute_b32 v229, v184, v90
	s_waitcnt lgkmcnt(0)
	v_bfi_b32 v196, v188, v229, v228
	ds_bpermute_b32 v228, v184, v103
	ds_bpermute_b32 v229, v184, v91
	s_waitcnt lgkmcnt(0)
	v_bfi_b32 v197, v188, v229, v228
	v_lshl_add_u64 v[178:179], v[168:169], 0, v[148:149]
	ds_bpermute_b32 v174, v184, v178
	ds_bpermute_b32 v175, v184, v179
	ds_bpermute_b32 v176, v185, v178
	ds_bpermute_b32 v177, v185, v179
	s_waitcnt lgkmcnt(0)
	v_lshl_add_u64 v[174:175], v[174:175], 0, v[186:187]
	v_lshl_add_u64 v[176:177], v[176:177], 0, v[186:187]
	global_load_dwordx4 v[204:207], v[174:175], off
	global_load_dwordx4 v[208:211], v[176:177], off
	global_load_dwordx4 v[212:215], v[174:175], off offset:512
	global_load_dwordx4 v[216:219], v[176:177], off offset:512
	ds_bpermute_b32 v228, v184, v142
	ds_bpermute_b32 v229, v184, v138
	ds_bpermute_b32 v230, v184, v143
	ds_bpermute_b32 v231, v184, v139
	s_waitcnt lgkmcnt(0)
	v_bfi_b32 v220, v188, v229, v228
	v_bfi_b32 v221, v188, v231, v230
	ds_bpermute_b32 v228, v184, v144
	ds_bpermute_b32 v229, v184, v140
	ds_bpermute_b32 v230, v184, v145
	ds_bpermute_b32 v231, v184, v141
	s_waitcnt lgkmcnt(0)
	v_bfi_b32 v222, v188, v229, v228
	v_bfi_b32 v223, v188, v231, v230
	ds_bpermute_b32 v228, v185, v142
	ds_bpermute_b32 v229, v185, v138
	ds_bpermute_b32 v230, v185, v143
	ds_bpermute_b32 v231, v185, v139
	s_waitcnt lgkmcnt(0)
	v_bfi_b32 v224, v188, v229, v228
	v_bfi_b32 v225, v188, v231, v230
	ds_bpermute_b32 v228, v185, v144
	ds_bpermute_b32 v229, v185, v140
	ds_bpermute_b32 v230, v185, v145
	ds_bpermute_b32 v231, v185, v141
	s_waitcnt lgkmcnt(0)
	v_bfi_b32 v226, v188, v229, v228
	v_bfi_b32 v227, v188, v231, v230
	s_waitcnt vmcnt(2)
	v_pk_fma_f32 v[206:207], v[222:223], v[192:193], v[206:207]
	v_pk_fma_f32 v[204:205], v[220:221], v[190:191], v[204:205]
	v_pk_fma_f32 v[210:211], v[226:227], v[192:193], v[210:211]
	v_pk_fma_f32 v[208:209], v[224:225], v[190:191], v[208:209]
	global_store_dwordx4 v[174:175], v[204:207], off
	global_store_dwordx4 v[176:177], v[208:211], off
	v_lshl_add_u64 v[178:179], v[168:169], 0, v[150:151]
	ds_bpermute_b32 v180, v184, v178
	ds_bpermute_b32 v181, v184, v179
	ds_bpermute_b32 v198, v185, v178
	ds_bpermute_b32 v199, v185, v179
	s_waitcnt lgkmcnt(0)
	v_lshl_add_u64 v[180:181], v[180:181], 0, v[186:187]
	v_lshl_add_u64 v[198:199], v[198:199], 0, v[186:187]
	global_load_dwordx4 v[204:207], v[180:181], off
	global_load_dwordx4 v[208:211], v[198:199], off
	ds_bpermute_b32 v228, v184, v134
	ds_bpermute_b32 v229, v184, v124
	ds_bpermute_b32 v230, v184, v135
	ds_bpermute_b32 v231, v184, v125
	s_waitcnt lgkmcnt(0)
	v_bfi_b32 v220, v188, v229, v228
	v_bfi_b32 v221, v188, v231, v230
	ds_bpermute_b32 v228, v184, v136
	ds_bpermute_b32 v229, v184, v126
	ds_bpermute_b32 v230, v184, v137
	ds_bpermute_b32 v231, v184, v127
	s_waitcnt lgkmcnt(0)
	v_bfi_b32 v222, v188, v229, v228
	v_bfi_b32 v223, v188, v231, v230
	ds_bpermute_b32 v228, v185, v134
	ds_bpermute_b32 v229, v185, v124
	ds_bpermute_b32 v230, v185, v135
	ds_bpermute_b32 v231, v185, v125
	s_waitcnt lgkmcnt(0)
	v_bfi_b32 v224, v188, v229, v228
	v_bfi_b32 v225, v188, v231, v230
	ds_bpermute_b32 v228, v185, v136
	ds_bpermute_b32 v229, v185, v126
	ds_bpermute_b32 v230, v185, v137
	ds_bpermute_b32 v231, v185, v127
	s_waitcnt lgkmcnt(0)
	v_bfi_b32 v226, v188, v229, v228
	v_bfi_b32 v227, v188, v231, v230
	s_waitcnt vmcnt(4)
	v_pk_fma_f32 v[214:215], v[222:223], v[196:197], v[214:215]
	v_pk_fma_f32 v[212:213], v[220:221], v[194:195], v[212:213]
	v_pk_fma_f32 v[218:219], v[226:227], v[196:197], v[218:219]
	v_pk_fma_f32 v[216:217], v[224:225], v[194:195], v[216:217]
	global_store_dwordx4 v[174:175], v[212:215], off offset:512
	global_store_dwordx4 v[176:177], v[216:219], off offset:512
	global_load_dwordx4 v[212:215], v[180:181], off offset:512
	global_load_dwordx4 v[216:219], v[198:199], off offset:512
	ds_bpermute_b32 v228, v184, v130
	ds_bpermute_b32 v229, v184, v120
	ds_bpermute_b32 v230, v184, v131
	ds_bpermute_b32 v231, v184, v121
	s_waitcnt lgkmcnt(0)
;     __device__ __forceinline__ void operator()(const pg8::f32x4 (&acc)[2][2][4][2], const pg8::Unit& u, int wr, int wc, int fr, int fq) const {
;     ...
;         for (int ai = 0; ai < 2; ++ai)
; #pragma unroll
;             for (int m = 0; m < 4; ++m) {
;                 float* rowp = base + (size_t)(ai * 128 + wr * 64 + m * 16 + fr) * DM + col0;
; #pragma unroll
;                 for (int bj = 0; bj < 2; ++bj)
; #pragma unroll
;                     for (int n = 0; n < 2; ++n) {
;                         pg8::f32x4* p = (pg8::f32x4*)(rowp + bj * 128 + n * 16);
;                         pg8::f32x4 xv = *p; xv = xv + gv[bj][n] * acc[ai][bj][m][n]; *p = xv;
;                     }
;                 if (m & 1) asm volatile("" ::: "memory");
	v_bfi_b32 v220, v188, v229, v228
	v_bfi_b32 v221, v188, v231, v230
	ds_bpermute_b32 v228, v184, v132
	ds_bpermute_b32 v229, v184, v122
	ds_bpermute_b32 v230, v184, v133
	ds_bpermute_b32 v231, v184, v123
	s_waitcnt lgkmcnt(0)
	v_bfi_b32 v222, v188, v229, v228
	v_bfi_b32 v223, v188, v231, v230
	ds_bpermute_b32 v228, v185, v130
	ds_bpermute_b32 v229, v185, v120
	ds_bpermute_b32 v230, v185, v131
	ds_bpermute_b32 v231, v185, v121
	s_waitcnt lgkmcnt(0)
	v_bfi_b32 v224, v188, v229, v228
	v_bfi_b32 v225, v188, v231, v230
	ds_bpermute_b32 v228, v185, v132
	ds_bpermute_b32 v229, v185, v122
	ds_bpermute_b32 v230, v185, v133
	ds_bpermute_b32 v231, v185, v123
	s_waitcnt lgkmcnt(0)
	v_bfi_b32 v226, v188, v229, v228
	v_bfi_b32 v227, v188, v231, v230
	s_waitcnt vmcnt(4)
	v_pk_fma_f32 v[206:207], v[222:223], v[192:193], v[206:207]
	v_pk_fma_f32 v[204:205], v[220:221], v[190:191], v[204:205]
	v_pk_fma_f32 v[210:211], v[226:227], v[192:193], v[210:211]
	v_pk_fma_f32 v[208:209], v[224:225], v[190:191], v[208:209]
	global_store_dwordx4 v[180:181], v[204:207], off
	global_store_dwordx4 v[198:199], v[208:211], off
	v_lshl_add_u64 v[178:179], v[168:169], 0, v[152:153]
	ds_bpermute_b32 v174, v184, v178
	ds_bpermute_b32 v175, v184, v179
	ds_bpermute_b32 v176, v185, v178
	ds_bpermute_b32 v177, v185, v179
	s_waitcnt lgkmcnt(0)
	v_lshl_add_u64 v[174:175], v[174:175], 0, v[186:187]
	v_lshl_add_u64 v[176:177], v[176:177], 0, v[186:187]
	global_load_dwordx4 v[204:207], v[174:175], off
	global_load_dwordx4 v[208:211], v[176:177], off
	ds_bpermute_b32 v228, v184, v116
	ds_bpermute_b32 v229, v184, v112
	ds_bpermute_b32 v230, v184, v117
	ds_bpermute_b32 v231, v184, v113
	s_waitcnt lgkmcnt(0)
	v_bfi_b32 v220, v188, v229, v228
	v_bfi_b32 v221, v188, v231, v230
	ds_bpermute_b32 v228, v184, v118
	ds_bpermute_b32 v229, v184, v114
	ds_bpermute_b32 v230, v184, v119
	ds_bpermute_b32 v231, v184, v115
	s_waitcnt lgkmcnt(0)
	v_bfi_b32 v222, v188, v229, v228
	v_bfi_b32 v223, v188, v231, v230
	ds_bpermute_b32 v228, v185, v116
	ds_bpermute_b32 v229, v185, v112
	ds_bpermute_b32 v230, v185, v117
	ds_bpermute_b32 v231, v185, v113
	s_waitcnt lgkmcnt(0)
	v_bfi_b32 v224, v188, v229, v228
	v_bfi_b32 v225, v188, v231, v230
	ds_bpermute_b32 v228, v185, v118
	ds_bpermute_b32 v229, v185, v114
	ds_bpermute_b32 v230, v185, v119
	ds_bpermute_b32 v231, v185, v115
	s_waitcnt lgkmcnt(0)
	v_bfi_b32 v226, v188, v229, v228
	v_bfi_b32 v227, v188, v231, v230
	s_waitcnt vmcnt(4)
	v_pk_fma_f32 v[214:215], v[222:223], v[196:197], v[214:215]
	v_pk_fma_f32 v[212:213], v[220:221], v[194:195], v[212:213]
	v_pk_fma_f32 v[218:219], v[226:227], v[196:197], v[218:219]
	v_pk_fma_f32 v[216:217], v[224:225], v[194:195], v[216:217]
	global_store_dwordx4 v[180:181], v[212:215], off offset:512
	global_store_dwordx4 v[198:199], v[216:219], off offset:512
	global_load_dwordx4 v[212:215], v[174:175], off offset:512
	global_load_dwordx4 v[216:219], v[176:177], off offset:512
	ds_bpermute_b32 v228, v184, v96
	ds_bpermute_b32 v229, v184, v92
	ds_bpermute_b32 v230, v184, v97
	ds_bpermute_b32 v231, v184, v93
	s_waitcnt lgkmcnt(0)
	v_bfi_b32 v220, v188, v229, v228
	v_bfi_b32 v221, v188, v231, v230
	ds_bpermute_b32 v228, v184, v98
	ds_bpermute_b32 v229, v184, v94
	ds_bpermute_b32 v230, v184, v99
	ds_bpermute_b32 v231, v184, v95
	s_waitcnt lgkmcnt(0)
	v_bfi_b32 v222, v188, v229, v228
	v_bfi_b32 v223, v188, v231, v230
	ds_bpermute_b32 v228, v185, v96
	ds_bpermute_b32 v229, v185, v92
	ds_bpermute_b32 v230, v185, v97
	ds_bpermute_b32 v231, v185, v93
	s_waitcnt lgkmcnt(0)
	v_bfi_b32 v224, v188, v229, v228
	v_bfi_b32 v225, v188, v231, v230
	ds_bpermute_b32 v228, v185, v98
	ds_bpermute_b32 v229, v185, v94
	ds_bpermute_b32 v230, v185, v99
	ds_bpermute_b32 v231, v185, v95
	s_waitcnt lgkmcnt(0)
	v_bfi_b32 v226, v188, v229, v228
	v_bfi_b32 v227, v188, v231, v230
	s_waitcnt vmcnt(4)
	v_pk_fma_f32 v[206:207], v[222:223], v[192:193], v[206:207]
	v_pk_fma_f32 v[204:205], v[220:221], v[190:191], v[204:205]
	v_pk_fma_f32 v[210:211], v[226:227], v[192:193], v[210:211]
	v_pk_fma_f32 v[208:209], v[224:225], v[190:191], v[208:209]
	global_store_dwordx4 v[174:175], v[204:207], off
	global_store_dwordx4 v[176:177], v[208:211], off
	v_lshl_add_u64 v[178:179], v[168:169], 0, v[154:155]
	ds_bpermute_b32 v180, v184, v178
	ds_bpermute_b32 v181, v184, v179
	ds_bpermute_b32 v198, v185, v178
	ds_bpermute_b32 v199, v185, v179
	s_waitcnt lgkmcnt(0)
	v_lshl_add_u64 v[180:181], v[180:181], 0, v[186:187]
	v_lshl_add_u64 v[198:199], v[198:199], 0, v[186:187]
	global_load_dwordx4 v[204:207], v[180:181], off
	global_load_dwordx4 v[208:211], v[198:199], off
	ds_bpermute_b32 v228, v184, v84
	ds_bpermute_b32 v229, v184, v76
	ds_bpermute_b32 v230, v184, v85
	ds_bpermute_b32 v231, v184, v77
	s_waitcnt lgkmcnt(0)
	v_bfi_b32 v220, v188, v229, v228
	v_bfi_b32 v221, v188, v231, v230
	ds_bpermute_b32 v228, v184, v86
	ds_bpermute_b32 v229, v184, v78
	ds_bpermute_b32 v230, v184, v87
	ds_bpermute_b32 v231, v184, v79
	s_waitcnt lgkmcnt(0)
	v_bfi_b32 v222, v188, v229, v228
	v_bfi_b32 v223, v188, v231, v230
	ds_bpermute_b32 v228, v185, v84
	ds_bpermute_b32 v229, v185, v76
	ds_bpermute_b32 v230, v185, v85
	ds_bpermute_b32 v231, v185, v77
	s_waitcnt lgkmcnt(0)
	v_bfi_b32 v224, v188, v229, v228
	v_bfi_b32 v225, v188, v231, v230
	ds_bpermute_b32 v228, v185, v86
	ds_bpermute_b32 v229, v185, v78
	ds_bpermute_b32 v230, v185, v87
	ds_bpermute_b32 v231, v185, v79
	s_waitcnt lgkmcnt(0)
	v_bfi_b32 v226, v188, v229, v228
	v_bfi_b32 v227, v188, v231, v230
	s_waitcnt vmcnt(4)
;     __device__ __forceinline__ void operator()(const pg8::f32x4 (&acc)[2][2][4][2], const pg8::Unit& u, int wr, int wc, int fr, int fq) const {
;     ...
;         for (int ai = 0; ai < 2; ++ai)
; #pragma unroll
;             for (int m = 0; m < 4; ++m) {
;                 float* rowp = base + (size_t)(ai * 128 + wr * 64 + m * 16 + fr) * DM + col0;
; #pragma unroll
;                 for (int bj = 0; bj < 2; ++bj)
; #pragma unroll
;                     for (int n = 0; n < 2; ++n) {
;                         pg8::f32x4* p = (pg8::f32x4*)(rowp + bj * 128 + n * 16);
;                         pg8::f32x4 xv = *p; xv = xv + gv[bj][n] * acc[ai][bj][m][n]; *p = xv;
;                     }
;                 if (m & 1) asm volatile("" ::: "memory");
	v_pk_fma_f32 v[214:215], v[222:223], v[196:197], v[214:215]
	v_pk_fma_f32 v[212:213], v[220:221], v[194:195], v[212:213]
	v_pk_fma_f32 v[218:219], v[226:227], v[196:197], v[218:219]
	v_pk_fma_f32 v[216:217], v[224:225], v[194:195], v[216:217]
	global_store_dwordx4 v[174:175], v[212:215], off offset:512
	global_store_dwordx4 v[176:177], v[216:219], off offset:512
	global_load_dwordx4 v[212:215], v[180:181], off offset:512
	global_load_dwordx4 v[216:219], v[198:199], off offset:512
	ds_bpermute_b32 v228, v184, v80
	ds_bpermute_b32 v229, v184, v72
	ds_bpermute_b32 v230, v184, v81
	ds_bpermute_b32 v231, v184, v73
	s_waitcnt lgkmcnt(0)
	v_bfi_b32 v220, v188, v229, v228
	v_bfi_b32 v221, v188, v231, v230
	ds_bpermute_b32 v228, v184, v82
	ds_bpermute_b32 v229, v184, v74
	ds_bpermute_b32 v230, v184, v83
	ds_bpermute_b32 v231, v184, v75
	s_waitcnt lgkmcnt(0)
	v_bfi_b32 v222, v188, v229, v228
	v_bfi_b32 v223, v188, v231, v230
	ds_bpermute_b32 v228, v185, v80
	ds_bpermute_b32 v229, v185, v72
	ds_bpermute_b32 v230, v185, v81
	ds_bpermute_b32 v231, v185, v73
	s_waitcnt lgkmcnt(0)
	v_bfi_b32 v224, v188, v229, v228
	v_bfi_b32 v225, v188, v231, v230
	ds_bpermute_b32 v228, v185, v82
	ds_bpermute_b32 v229, v185, v74
	ds_bpermute_b32 v230, v185, v83
	ds_bpermute_b32 v231, v185, v75
	s_waitcnt lgkmcnt(0)
	v_bfi_b32 v226, v188, v229, v228
	v_bfi_b32 v227, v188, v231, v230
	s_waitcnt vmcnt(4)
	v_pk_fma_f32 v[206:207], v[222:223], v[192:193], v[206:207]
	v_pk_fma_f32 v[204:205], v[220:221], v[190:191], v[204:205]
	v_pk_fma_f32 v[210:211], v[226:227], v[192:193], v[210:211]
	v_pk_fma_f32 v[208:209], v[224:225], v[190:191], v[208:209]
	global_store_dwordx4 v[180:181], v[204:207], off
	global_store_dwordx4 v[198:199], v[208:211], off
	v_lshl_add_u64 v[178:179], v[168:169], 0, v[156:157]
	ds_bpermute_b32 v174, v184, v178
	ds_bpermute_b32 v175, v184, v179
	ds_bpermute_b32 v176, v185, v178
	ds_bpermute_b32 v177, v185, v179
	s_waitcnt lgkmcnt(0)
	v_lshl_add_u64 v[174:175], v[174:175], 0, v[186:187]
	v_lshl_add_u64 v[176:177], v[176:177], 0, v[186:187]
	global_load_dwordx4 v[204:207], v[174:175], off
	global_load_dwordx4 v[208:211], v[176:177], off
	ds_bpermute_b32 v228, v184, v68
	ds_bpermute_b32 v229, v184, v64
	ds_bpermute_b32 v230, v184, v69
	ds_bpermute_b32 v231, v184, v65
	s_waitcnt lgkmcnt(0)
	v_bfi_b32 v220, v188, v229, v228
	v_bfi_b32 v221, v188, v231, v230
	ds_bpermute_b32 v228, v184, v70
	ds_bpermute_b32 v229, v184, v66
	ds_bpermute_b32 v230, v184, v71
	ds_bpermute_b32 v231, v184, v67
	s_waitcnt lgkmcnt(0)
	v_bfi_b32 v222, v188, v229, v228
	v_bfi_b32 v223, v188, v231, v230
	ds_bpermute_b32 v228, v185, v68
	ds_bpermute_b32 v229, v185, v64
	ds_bpermute_b32 v230, v185, v69
	ds_bpermute_b32 v231, v185, v65
	s_waitcnt lgkmcnt(0)
	v_bfi_b32 v224, v188, v229, v228
	v_bfi_b32 v225, v188, v231, v230
	ds_bpermute_b32 v228, v185, v70
	ds_bpermute_b32 v229, v185, v66
	ds_bpermute_b32 v230, v185, v71
	ds_bpermute_b32 v231, v185, v67
	s_waitcnt lgkmcnt(0)
	v_bfi_b32 v226, v188, v229, v228
	v_bfi_b32 v227, v188, v231, v230
	s_waitcnt vmcnt(4)
	v_pk_fma_f32 v[214:215], v[222:223], v[196:197], v[214:215]
	v_pk_fma_f32 v[212:213], v[220:221], v[194:195], v[212:213]
	v_pk_fma_f32 v[218:219], v[226:227], v[196:197], v[218:219]
	v_pk_fma_f32 v[216:217], v[224:225], v[194:195], v[216:217]
	global_store_dwordx4 v[180:181], v[212:215], off offset:512
	global_store_dwordx4 v[198:199], v[216:219], off offset:512
	global_load_dwordx4 v[212:215], v[174:175], off offset:512
	global_load_dwordx4 v[216:219], v[176:177], off offset:512
	ds_bpermute_b32 v228, v184, v60
	ds_bpermute_b32 v229, v184, v56
	ds_bpermute_b32 v230, v184, v61
	ds_bpermute_b32 v231, v184, v57
	s_waitcnt lgkmcnt(0)
	v_bfi_b32 v220, v188, v229, v228
	v_bfi_b32 v221, v188, v231, v230
	ds_bpermute_b32 v228, v184, v62
	ds_bpermute_b32 v229, v184, v58
	ds_bpermute_b32 v230, v184, v63
	ds_bpermute_b32 v231, v184, v59
	s_waitcnt lgkmcnt(0)
	v_bfi_b32 v222, v188, v229, v228
	v_bfi_b32 v223, v188, v231, v230
	ds_bpermute_b32 v228, v185, v60
	ds_bpermute_b32 v229, v185, v56
	ds_bpermute_b32 v230, v185, v61
	ds_bpermute_b32 v231, v185, v57
	s_waitcnt lgkmcnt(0)
	v_bfi_b32 v224, v188, v229, v228
	v_bfi_b32 v225, v188, v231, v230
	ds_bpermute_b32 v228, v185, v62
	ds_bpermute_b32 v229, v185, v58
	ds_bpermute_b32 v230, v185, v63
	ds_bpermute_b32 v231, v185, v59
	s_waitcnt lgkmcnt(0)
	v_bfi_b32 v226, v188, v229, v228
	v_bfi_b32 v227, v188, v231, v230
	s_waitcnt vmcnt(4)
	v_pk_fma_f32 v[206:207], v[222:223], v[192:193], v[206:207]
	v_pk_fma_f32 v[204:205], v[220:221], v[190:191], v[204:205]
	v_pk_fma_f32 v[210:211], v[226:227], v[192:193], v[210:211]
	v_pk_fma_f32 v[208:209], v[224:225], v[190:191], v[208:209]
	global_store_dwordx4 v[174:175], v[204:207], off
	global_store_dwordx4 v[176:177], v[208:211], off
	v_lshl_add_u64 v[178:179], v[168:169], 0, v[158:159]
	ds_bpermute_b32 v180, v184, v178
	ds_bpermute_b32 v181, v184, v179
	ds_bpermute_b32 v198, v185, v178
	ds_bpermute_b32 v199, v185, v179
	s_waitcnt lgkmcnt(0)
	v_lshl_add_u64 v[180:181], v[180:181], 0, v[186:187]
	v_lshl_add_u64 v[198:199], v[198:199], 0, v[186:187]
	global_load_dwordx4 v[204:207], v[180:181], off
	global_load_dwordx4 v[208:211], v[198:199], off
	ds_bpermute_b32 v228, v184, v52
	ds_bpermute_b32 v229, v184, v44
	ds_bpermute_b32 v230, v184, v53
	ds_bpermute_b32 v231, v184, v45
	s_waitcnt lgkmcnt(0)
	v_bfi_b32 v220, v188, v229, v228
	v_bfi_b32 v221, v188, v231, v230
	ds_bpermute_b32 v228, v184, v54
	ds_bpermute_b32 v229, v184, v46
	ds_bpermute_b32 v230, v184, v55
	ds_bpermute_b32 v231, v184, v47
	s_waitcnt lgkmcnt(0)
;     __device__ __forceinline__ void operator()(const pg8::f32x4 (&acc)[2][2][4][2], const pg8::Unit& u, int wr, int wc, int fr, int fq) const {
;     ...
;         for (int ai = 0; ai < 2; ++ai)
; #pragma unroll
;             for (int m = 0; m < 4; ++m) {
;                 float* rowp = base + (size_t)(ai * 128 + wr * 64 + m * 16 + fr) * DM + col0;
; #pragma unroll
;                 for (int bj = 0; bj < 2; ++bj)
; #pragma unroll
;                     for (int n = 0; n < 2; ++n) {
;                         pg8::f32x4* p = (pg8::f32x4*)(rowp + bj * 128 + n * 16);
;                         pg8::f32x4 xv = *p; xv = xv + gv[bj][n] * acc[ai][bj][m][n]; *p = xv;
;                     }
;                 if (m & 1) asm volatile("" ::: "memory");
	v_bfi_b32 v222, v188, v229, v228
	v_bfi_b32 v223, v188, v231, v230
	ds_bpermute_b32 v228, v185, v52
	ds_bpermute_b32 v229, v185, v44
	ds_bpermute_b32 v230, v185, v53
	ds_bpermute_b32 v231, v185, v45
	s_waitcnt lgkmcnt(0)
	v_bfi_b32 v224, v188, v229, v228
	v_bfi_b32 v225, v188, v231, v230
	ds_bpermute_b32 v228, v185, v54
	ds_bpermute_b32 v229, v185, v46
	ds_bpermute_b32 v230, v185, v55
	ds_bpermute_b32 v231, v185, v47
	s_waitcnt lgkmcnt(0)
	v_bfi_b32 v226, v188, v229, v228
	v_bfi_b32 v227, v188, v231, v230
	s_waitcnt vmcnt(4)
	v_pk_fma_f32 v[214:215], v[222:223], v[196:197], v[214:215]
	v_pk_fma_f32 v[212:213], v[220:221], v[194:195], v[212:213]
	v_pk_fma_f32 v[218:219], v[226:227], v[196:197], v[218:219]
	v_pk_fma_f32 v[216:217], v[224:225], v[194:195], v[216:217]
	global_store_dwordx4 v[174:175], v[212:215], off offset:512
	global_store_dwordx4 v[176:177], v[216:219], off offset:512
	global_load_dwordx4 v[212:215], v[180:181], off offset:512
	global_load_dwordx4 v[216:219], v[198:199], off offset:512
	ds_bpermute_b32 v228, v184, v48
	ds_bpermute_b32 v229, v184, v40
	ds_bpermute_b32 v230, v184, v49
	ds_bpermute_b32 v231, v184, v41
	s_waitcnt lgkmcnt(0)
	v_bfi_b32 v220, v188, v229, v228
	v_bfi_b32 v221, v188, v231, v230
	ds_bpermute_b32 v228, v184, v50
	ds_bpermute_b32 v229, v184, v42
	ds_bpermute_b32 v230, v184, v51
	ds_bpermute_b32 v231, v184, v43
	s_waitcnt lgkmcnt(0)
	v_bfi_b32 v222, v188, v229, v228
	v_bfi_b32 v223, v188, v231, v230
	ds_bpermute_b32 v228, v185, v48
	ds_bpermute_b32 v229, v185, v40
	ds_bpermute_b32 v230, v185, v49
	ds_bpermute_b32 v231, v185, v41
	s_waitcnt lgkmcnt(0)
	v_bfi_b32 v224, v188, v229, v228
	v_bfi_b32 v225, v188, v231, v230
	ds_bpermute_b32 v228, v185, v50
	ds_bpermute_b32 v229, v185, v42
	ds_bpermute_b32 v230, v185, v51
	ds_bpermute_b32 v231, v185, v43
	s_waitcnt lgkmcnt(0)
	v_bfi_b32 v226, v188, v229, v228
	v_bfi_b32 v227, v188, v231, v230
	s_waitcnt vmcnt(4)
	v_pk_fma_f32 v[206:207], v[222:223], v[192:193], v[206:207]
	v_pk_fma_f32 v[204:205], v[220:221], v[190:191], v[204:205]
	v_pk_fma_f32 v[210:211], v[226:227], v[192:193], v[210:211]
	v_pk_fma_f32 v[208:209], v[224:225], v[190:191], v[208:209]
	global_store_dwordx4 v[180:181], v[204:207], off
	global_store_dwordx4 v[198:199], v[208:211], off
	v_lshl_add_u64 v[178:179], v[168:169], 0, v[160:161]
	ds_bpermute_b32 v174, v184, v178
	ds_bpermute_b32 v175, v184, v179
	ds_bpermute_b32 v176, v185, v178
	ds_bpermute_b32 v177, v185, v179
	s_waitcnt lgkmcnt(0)
	v_lshl_add_u64 v[174:175], v[174:175], 0, v[186:187]
	v_lshl_add_u64 v[176:177], v[176:177], 0, v[186:187]
	global_load_dwordx4 v[204:207], v[174:175], off
	global_load_dwordx4 v[208:211], v[176:177], off
	ds_bpermute_b32 v228, v184, v36
	ds_bpermute_b32 v229, v184, v32
	ds_bpermute_b32 v230, v184, v37
	ds_bpermute_b32 v231, v184, v33
	s_waitcnt lgkmcnt(0)
	v_bfi_b32 v220, v188, v229, v228
	v_bfi_b32 v221, v188, v231, v230
	ds_bpermute_b32 v228, v184, v38
	ds_bpermute_b32 v229, v184, v34
	ds_bpermute_b32 v230, v184, v39
	ds_bpermute_b32 v231, v184, v35
	s_waitcnt lgkmcnt(0)
	v_bfi_b32 v222, v188, v229, v228
	v_bfi_b32 v223, v188, v231, v230
	ds_bpermute_b32 v228, v185, v36
	ds_bpermute_b32 v229, v185, v32
	ds_bpermute_b32 v230, v185, v37
	ds_bpermute_b32 v231, v185, v33
	s_waitcnt lgkmcnt(0)
	v_bfi_b32 v224, v188, v229, v228
	v_bfi_b32 v225, v188, v231, v230
	ds_bpermute_b32 v228, v185, v38
	ds_bpermute_b32 v229, v185, v34
	ds_bpermute_b32 v230, v185, v39
	ds_bpermute_b32 v231, v185, v35
	s_waitcnt lgkmcnt(0)
	v_bfi_b32 v226, v188, v229, v228
	v_bfi_b32 v227, v188, v231, v230
	s_waitcnt vmcnt(4)
	v_pk_fma_f32 v[214:215], v[222:223], v[196:197], v[214:215]
	v_pk_fma_f32 v[212:213], v[220:221], v[194:195], v[212:213]
	v_pk_fma_f32 v[218:219], v[226:227], v[196:197], v[218:219]
	v_pk_fma_f32 v[216:217], v[224:225], v[194:195], v[216:217]
	global_store_dwordx4 v[180:181], v[212:215], off offset:512
	global_store_dwordx4 v[198:199], v[216:219], off offset:512
	global_load_dwordx4 v[212:215], v[174:175], off offset:512
	global_load_dwordx4 v[216:219], v[176:177], off offset:512
	ds_bpermute_b32 v228, v184, v28
	ds_bpermute_b32 v229, v184, v24
	ds_bpermute_b32 v230, v184, v29
	ds_bpermute_b32 v231, v184, v25
	s_waitcnt lgkmcnt(0)
	v_bfi_b32 v220, v188, v229, v228
	v_bfi_b32 v221, v188, v231, v230
	ds_bpermute_b32 v228, v184, v30
	ds_bpermute_b32 v229, v184, v26
	ds_bpermute_b32 v230, v184, v31
	ds_bpermute_b32 v231, v184, v27
	s_waitcnt lgkmcnt(0)
	v_bfi_b32 v222, v188, v229, v228
	v_bfi_b32 v223, v188, v231, v230
	ds_bpermute_b32 v228, v185, v28
	ds_bpermute_b32 v229, v185, v24
	ds_bpermute_b32 v230, v185, v29
	ds_bpermute_b32 v231, v185, v25
	s_waitcnt lgkmcnt(0)
	v_bfi_b32 v224, v188, v229, v228
	v_bfi_b32 v225, v188, v231, v230
	ds_bpermute_b32 v228, v185, v30
	ds_bpermute_b32 v229, v185, v26
	ds_bpermute_b32 v230, v185, v31
	ds_bpermute_b32 v231, v185, v27
	s_waitcnt lgkmcnt(0)
;     __device__ __forceinline__ void operator()(const pg8::f32x4 (&acc)[2][2][4][2], const pg8::Unit& u, int wr, int wc, int fr, int fq) const {
;     ...
;         for (int ai = 0; ai < 2; ++ai)
; #pragma unroll
;             for (int m = 0; m < 4; ++m) {
;                 float* rowp = base + (size_t)(ai * 128 + wr * 64 + m * 16 + fr) * DM + col0;
; #pragma unroll
;                 for (int bj = 0; bj < 2; ++bj)
; #pragma unroll
;                     for (int n = 0; n < 2; ++n) {
;                         pg8::f32x4* p = (pg8::f32x4*)(rowp + bj * 128 + n * 16);
;                         pg8::f32x4 xv = *p; xv = xv + gv[bj][n] * acc[ai][bj][m][n]; *p = xv;
;                     }
;                 if (m & 1) asm volatile("" ::: "memory");
	v_bfi_b32 v226, v188, v229, v228
	v_bfi_b32 v227, v188, v231, v230
	s_waitcnt vmcnt(4)
	v_pk_fma_f32 v[206:207], v[222:223], v[192:193], v[206:207]
	v_pk_fma_f32 v[204:205], v[220:221], v[190:191], v[204:205]
	v_pk_fma_f32 v[210:211], v[226:227], v[192:193], v[210:211]
	v_pk_fma_f32 v[208:209], v[224:225], v[190:191], v[208:209]
	global_store_dwordx4 v[174:175], v[204:207], off
	global_store_dwordx4 v[176:177], v[208:211], off
	v_lshl_add_u64 v[178:179], v[168:169], 0, v[162:163]
	ds_bpermute_b32 v180, v184, v178
	ds_bpermute_b32 v181, v184, v179
	ds_bpermute_b32 v198, v185, v178
	ds_bpermute_b32 v199, v185, v179
	s_waitcnt lgkmcnt(0)
	v_lshl_add_u64 v[180:181], v[180:181], 0, v[186:187]
	v_lshl_add_u64 v[198:199], v[198:199], 0, v[186:187]
	global_load_dwordx4 v[204:207], v[180:181], off
	global_load_dwordx4 v[208:211], v[198:199], off
	ds_bpermute_b32 v228, v184, v20
	ds_bpermute_b32 v229, v184, v12
	ds_bpermute_b32 v230, v184, v21
	ds_bpermute_b32 v231, v184, v13
	s_waitcnt lgkmcnt(0)
	v_bfi_b32 v220, v188, v229, v228
	v_bfi_b32 v221, v188, v231, v230
	ds_bpermute_b32 v228, v184, v22
	ds_bpermute_b32 v229, v184, v14
	ds_bpermute_b32 v230, v184, v23
	ds_bpermute_b32 v231, v184, v15
	s_waitcnt lgkmcnt(0)
	v_bfi_b32 v222, v188, v229, v228
	v_bfi_b32 v223, v188, v231, v230
	ds_bpermute_b32 v228, v185, v20
	ds_bpermute_b32 v229, v185, v12
	ds_bpermute_b32 v230, v185, v21
	ds_bpermute_b32 v231, v185, v13
	s_waitcnt lgkmcnt(0)
	v_bfi_b32 v224, v188, v229, v228
	v_bfi_b32 v225, v188, v231, v230
	ds_bpermute_b32 v228, v185, v22
	ds_bpermute_b32 v229, v185, v14
	ds_bpermute_b32 v230, v185, v23
	ds_bpermute_b32 v231, v185, v15
	s_waitcnt lgkmcnt(0)
	v_bfi_b32 v226, v188, v229, v228
	v_bfi_b32 v227, v188, v231, v230
	s_waitcnt vmcnt(4)
	v_pk_fma_f32 v[214:215], v[222:223], v[196:197], v[214:215]
	v_pk_fma_f32 v[212:213], v[220:221], v[194:195], v[212:213]
	v_pk_fma_f32 v[218:219], v[226:227], v[196:197], v[218:219]
	v_pk_fma_f32 v[216:217], v[224:225], v[194:195], v[216:217]
	global_store_dwordx4 v[174:175], v[212:215], off offset:512
	global_store_dwordx4 v[176:177], v[216:219], off offset:512
	global_load_dwordx4 v[212:215], v[180:181], off offset:512
	global_load_dwordx4 v[216:219], v[198:199], off offset:512
	ds_bpermute_b32 v228, v184, v16
	ds_bpermute_b32 v229, v184, v8
	ds_bpermute_b32 v230, v184, v17
	ds_bpermute_b32 v231, v184, v9
	s_waitcnt lgkmcnt(0)
	v_bfi_b32 v220, v188, v229, v228
	v_bfi_b32 v221, v188, v231, v230
	ds_bpermute_b32 v228, v184, v18
	ds_bpermute_b32 v229, v184, v10
	ds_bpermute_b32 v230, v184, v19
	ds_bpermute_b32 v231, v184, v11
	s_waitcnt lgkmcnt(0)
	v_bfi_b32 v222, v188, v229, v228
	v_bfi_b32 v223, v188, v231, v230
	ds_bpermute_b32 v228, v185, v16
	ds_bpermute_b32 v229, v185, v8
	ds_bpermute_b32 v230, v185, v17
	ds_bpermute_b32 v231, v185, v9
	s_waitcnt lgkmcnt(0)
	v_bfi_b32 v224, v188, v229, v228
	v_bfi_b32 v225, v188, v231, v230
	ds_bpermute_b32 v228, v185, v18
	ds_bpermute_b32 v229, v185, v10
	ds_bpermute_b32 v230, v185, v19
	ds_bpermute_b32 v231, v185, v11
	s_waitcnt lgkmcnt(0)
	v_bfi_b32 v226, v188, v229, v228
	v_bfi_b32 v227, v188, v231, v230
	s_waitcnt vmcnt(4)
	v_pk_fma_f32 v[206:207], v[222:223], v[192:193], v[206:207]
	v_pk_fma_f32 v[204:205], v[220:221], v[190:191], v[204:205]
	v_pk_fma_f32 v[210:211], v[226:227], v[192:193], v[210:211]
	v_pk_fma_f32 v[208:209], v[224:225], v[190:191], v[208:209]
	global_store_dwordx4 v[180:181], v[204:207], off
	global_store_dwordx4 v[198:199], v[208:211], off
	ds_bpermute_b32 v228, v184, v4
	ds_bpermute_b32 v229, v184, v0
	ds_bpermute_b32 v230, v184, v5
	ds_bpermute_b32 v231, v184, v1
	s_waitcnt lgkmcnt(0)
	v_bfi_b32 v220, v188, v229, v228
	v_bfi_b32 v221, v188, v231, v230
	ds_bpermute_b32 v228, v184, v6
	ds_bpermute_b32 v229, v184, v2
	ds_bpermute_b32 v230, v184, v7
	ds_bpermute_b32 v231, v184, v3
	s_waitcnt lgkmcnt(0)
	v_bfi_b32 v222, v188, v229, v228
	v_bfi_b32 v223, v188, v231, v230
	ds_bpermute_b32 v228, v185, v4
	ds_bpermute_b32 v229, v185, v0
	ds_bpermute_b32 v230, v185, v5
	ds_bpermute_b32 v231, v185, v1
	s_waitcnt lgkmcnt(0)
	v_bfi_b32 v224, v188, v229, v228
	v_bfi_b32 v225, v188, v231, v230
	ds_bpermute_b32 v228, v185, v6
	ds_bpermute_b32 v229, v185, v2
	ds_bpermute_b32 v230, v185, v7
	ds_bpermute_b32 v231, v185, v3
	s_waitcnt lgkmcnt(0)
	v_bfi_b32 v226, v188, v229, v228
	v_bfi_b32 v227, v188, v231, v230
	s_waitcnt vmcnt(2)
	v_pk_fma_f32 v[214:215], v[222:223], v[196:197], v[214:215]
	v_pk_fma_f32 v[212:213], v[220:221], v[194:195], v[212:213]
	v_pk_fma_f32 v[218:219], v[226:227], v[196:197], v[218:219]
	v_pk_fma_f32 v[216:217], v[224:225], v[194:195], v[216:217]
	global_store_dwordx4 v[180:181], v[212:215], off offset:512
	global_store_dwordx4 v[198:199], v[216:219], off offset:512
	s_cbranch_vccnz .LBB0_1085
	s_andn2_b64 vcc, exec, s[0:1]
	s_cbranch_vccnz .LBB0_1084
	s_barrier
	s_branch .LBB0_1084

;     __device__ __forceinline__ void operator()(const pg8::f32x4 (&acc)[2][2][4][2], const pg8::Unit& u, int wr, int wc, int fr, int fq) const {
;         const int b = u.pm / 9, j = u.pm - b * 9;
;         float* base = (j == 0) ? xc + (size_t)b * CTX * DM : out + ((size_t)b * SEQ + (size_t)(j - 1) * 256) * DM;
;         const float* g = gate + (size_t)((j == 0) ? 16 : b) * MODW;
;         const int col0 = u.pn * 256 + wc * 32 + 4 * fq;
;         pg8::f32x4 gv[2][2];
; #pragma unroll
;         for (int bj = 0; bj < 2; ++bj)
; #pragma unroll
;             for (int n = 0; n < 2; ++n) gv[bj][n] = *(const pg8::f32x4*)(g + col0 + bj * 128 + n * 16);
; #pragma unroll
;         for (int ai = 0; ai < 2; ++ai)
; #pragma unroll
;             for (int m = 0; m < 4; ++m) {
;                 float* rowp = base + (size_t)(ai * 128 + wr * 64 + m * 16 + fr) * DM + col0;
; #pragma unroll
;                 for (int bj = 0; bj < 2; ++bj)
; #pragma unroll
;                     for (int n = 0; n < 2; ++n) {
;                         pg8::f32x4* p = (pg8::f32x4*)(rowp + bj * 128 + n * 16);
;                         pg8::f32x4 xv = *p; xv = xv + gv[bj][n] * acc[ai][bj][m][n]; *p = xv;
;                     }
.LBB0_1129:
	s_lshl_b64 s[12:13], s[56:57], 2
	v_lshl_or_b32 v88, s15, 8, v171
	s_add_u32 s12, s11, s12
	v_ashrrev_i32_e32 v89, 31, v88
	s_addc_u32 s13, s24, s13
	v_lshlrev_b64 v[168:169], 2, v[88:89]
	v_lshl_add_u64 v[88:89], s[12:13], 0, v[168:169]
	v_lshl_add_u64 v[168:169], s[48:49], 0, v[168:169]
	v_lshl_add_u64 v[178:179], v[168:169], 0, v[148:149]
	global_load_dwordx4 v[108:111], v[88:89], off
	global_load_dwordx4 v[104:107], v[88:89], off offset:64
	global_load_dwordx4 v[100:103], v[88:89], off offset:512
	s_nop 0
	global_load_dwordx4 v[88:91], v[88:89], off offset:576
	s_mov_b64 s[48:49], -1
	s_and_b64 vcc, exec, s[38:39]
	s_waitcnt vmcnt(0)
	v_and_b32_e32 v228, 63, v200
	v_lshrrev_b32_e32 v229, 3, v228
	v_and_b32_e32 v184, 3, v228
	v_lshl_or_b32 v184, v184, 4, v229
	v_lshlrev_b32_e32 v184, 2, v184
	v_add_u32_e32 v185, 32, v184
	v_bfe_u32 v229, v228, 2, 1
	v_lshlrev_b32_e32 v186, 6, v229
	v_mov_b32_e32 v187, 0
	v_sub_u32_e32 v188, 0, v229
	ds_bpermute_b32 v228, v184, v108
	ds_bpermute_b32 v229, v184, v104
	s_waitcnt lgkmcnt(0)
	v_bfi_b32 v190, v188, v229, v228
	ds_bpermute_b32 v228, v184, v109
	ds_bpermute_b32 v229, v184, v105
	s_waitcnt lgkmcnt(0)
	v_bfi_b32 v191, v188, v229, v228
	ds_bpermute_b32 v228, v184, v110
	ds_bpermute_b32 v229, v184, v106
	s_waitcnt lgkmcnt(0)
	v_bfi_b32 v192, v188, v229, v228
	ds_bpermute_b32 v228, v184, v111
	ds_bpermute_b32 v229, v184, v107
	s_waitcnt lgkmcnt(0)
	v_bfi_b32 v193, v188, v229, v228
	ds_bpermute_b32 v228, v184, v100
	ds_bpermute_b32 v229, v184, v88
	s_waitcnt lgkmcnt(0)
	v_bfi_b32 v194, v188, v229, v228
	ds_bpermute_b32 v228, v184, v101
	ds_bpermute_b32 v229, v184, v89
	s_waitcnt lgkmcnt(0)
	v_bfi_b32 v195, v188, v229, v228
	ds_bpermute_b32 v228, v184, v102
	ds_bpermute_b32 v229, v184, v90
	s_waitcnt lgkmcnt(0)
	v_bfi_b32 v196, v188, v229, v228
	ds_bpermute_b32 v228, v184, v103
	ds_bpermute_b32 v229, v184, v91
	s_waitcnt lgkmcnt(0)
	v_bfi_b32 v197, v188, v229, v228
	v_lshl_add_u64 v[178:179], v[168:169], 0, v[148:149]
	ds_bpermute_b32 v174, v184, v178
	ds_bpermute_b32 v175, v184, v179
	ds_bpermute_b32 v176, v185, v178
	ds_bpermute_b32 v177, v185, v179
	s_waitcnt lgkmcnt(0)
	v_lshl_add_u64 v[174:175], v[174:175], 0, v[186:187]
	v_lshl_add_u64 v[176:177], v[176:177], 0, v[186:187]
	global_load_dwordx4 v[204:207], v[174:175], off
	global_load_dwordx4 v[208:211], v[176:177], off
	global_load_dwordx4 v[212:215], v[174:175], off offset:512
	global_load_dwordx4 v[216:219], v[176:177], off offset:512
	ds_bpermute_b32 v228, v184, v142
	ds_bpermute_b32 v229, v184, v138
	ds_bpermute_b32 v230, v184, v143
	ds_bpermute_b32 v231, v184, v139
	s_waitcnt lgkmcnt(0)
	v_bfi_b32 v220, v188, v229, v228
	v_bfi_b32 v221, v188, v231, v230
	ds_bpermute_b32 v228, v184, v144
	ds_bpermute_b32 v229, v184, v140
	ds_bpermute_b32 v230, v184, v145
	ds_bpermute_b32 v231, v184, v141
	s_waitcnt lgkmcnt(0)
	v_bfi_b32 v222, v188, v229, v228
	v_bfi_b32 v223, v188, v231, v230
	ds_bpermute_b32 v228, v185, v142
	ds_bpermute_b32 v229, v185, v138
	ds_bpermute_b32 v230, v185, v143
	ds_bpermute_b32 v231, v185, v139
	s_waitcnt lgkmcnt(0)
	v_bfi_b32 v224, v188, v229, v228
	v_bfi_b32 v225, v188, v231, v230
	ds_bpermute_b32 v228, v185, v144
	ds_bpermute_b32 v229, v185, v140
	ds_bpermute_b32 v230, v185, v145
	ds_bpermute_b32 v231, v185, v141
	s_waitcnt lgkmcnt(0)
	v_bfi_b32 v226, v188, v229, v228
	v_bfi_b32 v227, v188, v231, v230
	s_waitcnt vmcnt(2)
	v_pk_fma_f32 v[206:207], v[222:223], v[192:193], v[206:207]
	v_pk_fma_f32 v[204:205], v[220:221], v[190:191], v[204:205]
	v_pk_fma_f32 v[210:211], v[226:227], v[192:193], v[210:211]
	v_pk_fma_f32 v[208:209], v[224:225], v[190:191], v[208:209]
	global_store_dwordx4 v[174:175], v[204:207], off
	global_store_dwordx4 v[176:177], v[208:211], off
	v_lshl_add_u64 v[178:179], v[168:169], 0, v[150:151]
	ds_bpermute_b32 v180, v184, v178
	ds_bpermute_b32 v181, v184, v179
	ds_bpermute_b32 v198, v185, v178
	ds_bpermute_b32 v199, v185, v179
	s_waitcnt lgkmcnt(0)
	v_lshl_add_u64 v[180:181], v[180:181], 0, v[186:187]
	v_lshl_add_u64 v[198:199], v[198:199], 0, v[186:187]
	global_load_dwordx4 v[204:207], v[180:181], off
	global_load_dwordx4 v[208:211], v[198:199], off
	ds_bpermute_b32 v228, v184, v134
	ds_bpermute_b32 v229, v184, v124
	ds_bpermute_b32 v230, v184, v135
	ds_bpermute_b32 v231, v184, v125
	s_waitcnt lgkmcnt(0)
	v_bfi_b32 v220, v188, v229, v228
	v_bfi_b32 v221, v188, v231, v230
	ds_bpermute_b32 v228, v184, v136
	ds_bpermute_b32 v229, v184, v126
	ds_bpermute_b32 v230, v184, v137
	ds_bpermute_b32 v231, v184, v127
	s_waitcnt lgkmcnt(0)
	v_bfi_b32 v222, v188, v229, v228
	v_bfi_b32 v223, v188, v231, v230
	ds_bpermute_b32 v228, v185, v134
	ds_bpermute_b32 v229, v185, v124
	ds_bpermute_b32 v230, v185, v135
	ds_bpermute_b32 v231, v185, v125
	s_waitcnt lgkmcnt(0)
	v_bfi_b32 v224, v188, v229, v228
	v_bfi_b32 v225, v188, v231, v230
	ds_bpermute_b32 v228, v185, v136
	ds_bpermute_b32 v229, v185, v126
	ds_bpermute_b32 v230, v185, v137
	ds_bpermute_b32 v231, v185, v127
	s_waitcnt lgkmcnt(0)
	v_bfi_b32 v226, v188, v229, v228
	v_bfi_b32 v227, v188, v231, v230
	s_waitcnt vmcnt(4)
	v_pk_fma_f32 v[214:215], v[222:223], v[196:197], v[214:215]
	v_pk_fma_f32 v[212:213], v[220:221], v[194:195], v[212:213]
	v_pk_fma_f32 v[218:219], v[226:227], v[196:197], v[218:219]
	v_pk_fma_f32 v[216:217], v[224:225], v[194:195], v[216:217]
	global_store_dwordx4 v[174:175], v[212:215], off offset:512
	global_store_dwordx4 v[176:177], v[216:219], off offset:512
	global_load_dwordx4 v[212:215], v[180:181], off offset:512
	global_load_dwordx4 v[216:219], v[198:199], off offset:512
	ds_bpermute_b32 v228, v184, v130
	ds_bpermute_b32 v229, v184, v120
	ds_bpermute_b32 v230, v184, v131
	ds_bpermute_b32 v231, v184, v121
	s_waitcnt lgkmcnt(0)
;     __device__ __forceinline__ void operator()(const pg8::f32x4 (&acc)[2][2][4][2], const pg8::Unit& u, int wr, int wc, int fr, int fq) const {
;     ...
;         for (int ai = 0; ai < 2; ++ai)
; #pragma unroll
;             for (int m = 0; m < 4; ++m) {
;                 float* rowp = base + (size_t)(ai * 128 + wr * 64 + m * 16 + fr) * DM + col0;
; #pragma unroll
;                 for (int bj = 0; bj < 2; ++bj)
; #pragma unroll
;                     for (int n = 0; n < 2; ++n) {
;                         pg8::f32x4* p = (pg8::f32x4*)(rowp + bj * 128 + n * 16);
;                         pg8::f32x4 xv = *p; xv = xv + gv[bj][n] * acc[ai][bj][m][n]; *p = xv;
;                     }
;                 if (m & 1) asm volatile("" ::: "memory");
	v_bfi_b32 v220, v188, v229, v228
	v_bfi_b32 v221, v188, v231, v230
	ds_bpermute_b32 v228, v184, v132
	ds_bpermute_b32 v229, v184, v122
	ds_bpermute_b32 v230, v184, v133
	ds_bpermute_b32 v231, v184, v123
	s_waitcnt lgkmcnt(0)
	v_bfi_b32 v222, v188, v229, v228
	v_bfi_b32 v223, v188, v231, v230
	ds_bpermute_b32 v228, v185, v130
	ds_bpermute_b32 v229, v185, v120
	ds_bpermute_b32 v230, v185, v131
	ds_bpermute_b32 v231, v185, v121
	s_waitcnt lgkmcnt(0)
	v_bfi_b32 v224, v188, v229, v228
	v_bfi_b32 v225, v188, v231, v230
	ds_bpermute_b32 v228, v185, v132
	ds_bpermute_b32 v229, v185, v122
	ds_bpermute_b32 v230, v185, v133
	ds_bpermute_b32 v231, v185, v123
	s_waitcnt lgkmcnt(0)
	v_bfi_b32 v226, v188, v229, v228
	v_bfi_b32 v227, v188, v231, v230
	s_waitcnt vmcnt(4)
	v_pk_fma_f32 v[206:207], v[222:223], v[192:193], v[206:207]
	v_pk_fma_f32 v[204:205], v[220:221], v[190:191], v[204:205]
	v_pk_fma_f32 v[210:211], v[226:227], v[192:193], v[210:211]
	v_pk_fma_f32 v[208:209], v[224:225], v[190:191], v[208:209]
	global_store_dwordx4 v[180:181], v[204:207], off
	global_store_dwordx4 v[198:199], v[208:211], off
	v_lshl_add_u64 v[178:179], v[168:169], 0, v[152:153]
	ds_bpermute_b32 v174, v184, v178
	ds_bpermute_b32 v175, v184, v179
	ds_bpermute_b32 v176, v185, v178
	ds_bpermute_b32 v177, v185, v179
	s_waitcnt lgkmcnt(0)
	v_lshl_add_u64 v[174:175], v[174:175], 0, v[186:187]
	v_lshl_add_u64 v[176:177], v[176:177], 0, v[186:187]
	global_load_dwordx4 v[204:207], v[174:175], off
	global_load_dwordx4 v[208:211], v[176:177], off
	ds_bpermute_b32 v228, v184, v116
	ds_bpermute_b32 v229, v184, v112
	ds_bpermute_b32 v230, v184, v117
	ds_bpermute_b32 v231, v184, v113
	s_waitcnt lgkmcnt(0)
	v_bfi_b32 v220, v188, v229, v228
	v_bfi_b32 v221, v188, v231, v230
	ds_bpermute_b32 v228, v184, v118
	ds_bpermute_b32 v229, v184, v114
	ds_bpermute_b32 v230, v184, v119
	ds_bpermute_b32 v231, v184, v115
	s_waitcnt lgkmcnt(0)
	v_bfi_b32 v222, v188, v229, v228
	v_bfi_b32 v223, v188, v231, v230
	ds_bpermute_b32 v228, v185, v116
	ds_bpermute_b32 v229, v185, v112
	ds_bpermute_b32 v230, v185, v117
	ds_bpermute_b32 v231, v185, v113
	s_waitcnt lgkmcnt(0)
	v_bfi_b32 v224, v188, v229, v228
	v_bfi_b32 v225, v188, v231, v230
	ds_bpermute_b32 v228, v185, v118
	ds_bpermute_b32 v229, v185, v114
	ds_bpermute_b32 v230, v185, v119
	ds_bpermute_b32 v231, v185, v115
	s_waitcnt lgkmcnt(0)
	v_bfi_b32 v226, v188, v229, v228
	v_bfi_b32 v227, v188, v231, v230
	s_waitcnt vmcnt(4)
	v_pk_fma_f32 v[214:215], v[222:223], v[196:197], v[214:215]
	v_pk_fma_f32 v[212:213], v[220:221], v[194:195], v[212:213]
	v_pk_fma_f32 v[218:219], v[226:227], v[196:197], v[218:219]
	v_pk_fma_f32 v[216:217], v[224:225], v[194:195], v[216:217]
	global_store_dwordx4 v[180:181], v[212:215], off offset:512
	global_store_dwordx4 v[198:199], v[216:219], off offset:512
	global_load_dwordx4 v[212:215], v[174:175], off offset:512
	global_load_dwordx4 v[216:219], v[176:177], off offset:512
	ds_bpermute_b32 v228, v184, v96
	ds_bpermute_b32 v229, v184, v92
	ds_bpermute_b32 v230, v184, v97
	ds_bpermute_b32 v231, v184, v93
	s_waitcnt lgkmcnt(0)
	v_bfi_b32 v220, v188, v229, v228
	v_bfi_b32 v221, v188, v231, v230
	ds_bpermute_b32 v228, v184, v98
	ds_bpermute_b32 v229, v184, v94
	ds_bpermute_b32 v230, v184, v99
	ds_bpermute_b32 v231, v184, v95
	s_waitcnt lgkmcnt(0)
	v_bfi_b32 v222, v188, v229, v228
	v_bfi_b32 v223, v188, v231, v230
	ds_bpermute_b32 v228, v185, v96
	ds_bpermute_b32 v229, v185, v92
	ds_bpermute_b32 v230, v185, v97
	ds_bpermute_b32 v231, v185, v93
	s_waitcnt lgkmcnt(0)
	v_bfi_b32 v224, v188, v229, v228
	v_bfi_b32 v225, v188, v231, v230
	ds_bpermute_b32 v228, v185, v98
	ds_bpermute_b32 v229, v185, v94
	ds_bpermute_b32 v230, v185, v99
	ds_bpermute_b32 v231, v185, v95
	s_waitcnt lgkmcnt(0)
	v_bfi_b32 v226, v188, v229, v228
	v_bfi_b32 v227, v188, v231, v230
	s_waitcnt vmcnt(4)
	v_pk_fma_f32 v[206:207], v[222:223], v[192:193], v[206:207]
	v_pk_fma_f32 v[204:205], v[220:221], v[190:191], v[204:205]
	v_pk_fma_f32 v[210:211], v[226:227], v[192:193], v[210:211]
	v_pk_fma_f32 v[208:209], v[224:225], v[190:191], v[208:209]
	global_store_dwordx4 v[174:175], v[204:207], off
	global_store_dwordx4 v[176:177], v[208:211], off
	v_lshl_add_u64 v[178:179], v[168:169], 0, v[154:155]
	ds_bpermute_b32 v180, v184, v178
	ds_bpermute_b32 v181, v184, v179
	ds_bpermute_b32 v198, v185, v178
	ds_bpermute_b32 v199, v185, v179
	s_waitcnt lgkmcnt(0)
	v_lshl_add_u64 v[180:181], v[180:181], 0, v[186:187]
	v_lshl_add_u64 v[198:199], v[198:199], 0, v[186:187]
	global_load_dwordx4 v[204:207], v[180:181], off
	global_load_dwordx4 v[208:211], v[198:199], off
	ds_bpermute_b32 v228, v184, v84
	ds_bpermute_b32 v229, v184, v76
	ds_bpermute_b32 v230, v184, v85
	ds_bpermute_b32 v231, v184, v77
	s_waitcnt lgkmcnt(0)
	v_bfi_b32 v220, v188, v229, v228
	v_bfi_b32 v221, v188, v231, v230
	ds_bpermute_b32 v228, v184, v86
	ds_bpermute_b32 v229, v184, v78
	ds_bpermute_b32 v230, v184, v87
	ds_bpermute_b32 v231, v184, v79
	s_waitcnt lgkmcnt(0)
	v_bfi_b32 v222, v188, v229, v228
	v_bfi_b32 v223, v188, v231, v230
	ds_bpermute_b32 v228, v185, v84
	ds_bpermute_b32 v229, v185, v76
	ds_bpermute_b32 v230, v185, v85
	ds_bpermute_b32 v231, v185, v77
	s_waitcnt lgkmcnt(0)
	v_bfi_b32 v224, v188, v229, v228
	v_bfi_b32 v225, v188, v231, v230
	ds_bpermute_b32 v228, v185, v86
	ds_bpermute_b32 v229, v185, v78
	ds_bpermute_b32 v230, v185, v87
	ds_bpermute_b32 v231, v185, v79
	s_waitcnt lgkmcnt(0)
	v_bfi_b32 v226, v188, v229, v228
	v_bfi_b32 v227, v188, v231, v230
	s_waitcnt vmcnt(4)
;     __device__ __forceinline__ void operator()(const pg8::f32x4 (&acc)[2][2][4][2], const pg8::Unit& u, int wr, int wc, int fr, int fq) const {
;     ...
;         for (int ai = 0; ai < 2; ++ai)
; #pragma unroll
;             for (int m = 0; m < 4; ++m) {
;                 float* rowp = base + (size_t)(ai * 128 + wr * 64 + m * 16 + fr) * DM + col0;
; #pragma unroll
;                 for (int bj = 0; bj < 2; ++bj)
; #pragma unroll
;                     for (int n = 0; n < 2; ++n) {
;                         pg8::f32x4* p = (pg8::f32x4*)(rowp + bj * 128 + n * 16);
;                         pg8::f32x4 xv = *p; xv = xv + gv[bj][n] * acc[ai][bj][m][n]; *p = xv;
;                     }
;                 if (m & 1) asm volatile("" ::: "memory");
	v_pk_fma_f32 v[214:215], v[222:223], v[196:197], v[214:215]
	v_pk_fma_f32 v[212:213], v[220:221], v[194:195], v[212:213]
	v_pk_fma_f32 v[218:219], v[226:227], v[196:197], v[218:219]
	v_pk_fma_f32 v[216:217], v[224:225], v[194:195], v[216:217]
	global_store_dwordx4 v[174:175], v[212:215], off offset:512
	global_store_dwordx4 v[176:177], v[216:219], off offset:512
	global_load_dwordx4 v[212:215], v[180:181], off offset:512
	global_load_dwordx4 v[216:219], v[198:199], off offset:512
	ds_bpermute_b32 v228, v184, v80
	ds_bpermute_b32 v229, v184, v72
	ds_bpermute_b32 v230, v184, v81
	ds_bpermute_b32 v231, v184, v73
	s_waitcnt lgkmcnt(0)
	v_bfi_b32 v220, v188, v229, v228
	v_bfi_b32 v221, v188, v231, v230
	ds_bpermute_b32 v228, v184, v82
	ds_bpermute_b32 v229, v184, v74
	ds_bpermute_b32 v230, v184, v83
	ds_bpermute_b32 v231, v184, v75
	s_waitcnt lgkmcnt(0)
	v_bfi_b32 v222, v188, v229, v228
	v_bfi_b32 v223, v188, v231, v230
	ds_bpermute_b32 v228, v185, v80
	ds_bpermute_b32 v229, v185, v72
	ds_bpermute_b32 v230, v185, v81
	ds_bpermute_b32 v231, v185, v73
	s_waitcnt lgkmcnt(0)
	v_bfi_b32 v224, v188, v229, v228
	v_bfi_b32 v225, v188, v231, v230
	ds_bpermute_b32 v228, v185, v82
	ds_bpermute_b32 v229, v185, v74
	ds_bpermute_b32 v230, v185, v83
	ds_bpermute_b32 v231, v185, v75
	s_waitcnt lgkmcnt(0)
	v_bfi_b32 v226, v188, v229, v228
	v_bfi_b32 v227, v188, v231, v230
	s_waitcnt vmcnt(4)
	v_pk_fma_f32 v[206:207], v[222:223], v[192:193], v[206:207]
	v_pk_fma_f32 v[204:205], v[220:221], v[190:191], v[204:205]
	v_pk_fma_f32 v[210:211], v[226:227], v[192:193], v[210:211]
	v_pk_fma_f32 v[208:209], v[224:225], v[190:191], v[208:209]
	global_store_dwordx4 v[180:181], v[204:207], off
	global_store_dwordx4 v[198:199], v[208:211], off
	v_lshl_add_u64 v[178:179], v[168:169], 0, v[156:157]
	ds_bpermute_b32 v174, v184, v178
	ds_bpermute_b32 v175, v184, v179
	ds_bpermute_b32 v176, v185, v178
	ds_bpermute_b32 v177, v185, v179
	s_waitcnt lgkmcnt(0)
	v_lshl_add_u64 v[174:175], v[174:175], 0, v[186:187]
	v_lshl_add_u64 v[176:177], v[176:177], 0, v[186:187]
	global_load_dwordx4 v[204:207], v[174:175], off
	global_load_dwordx4 v[208:211], v[176:177], off
	ds_bpermute_b32 v228, v184, v68
	ds_bpermute_b32 v229, v184, v64
	ds_bpermute_b32 v230, v184, v69
	ds_bpermute_b32 v231, v184, v65
	s_waitcnt lgkmcnt(0)
	v_bfi_b32 v220, v188, v229, v228
	v_bfi_b32 v221, v188, v231, v230
	ds_bpermute_b32 v228, v184, v70
	ds_bpermute_b32 v229, v184, v66
	ds_bpermute_b32 v230, v184, v71
	ds_bpermute_b32 v231, v184, v67
	s_waitcnt lgkmcnt(0)
	v_bfi_b32 v222, v188, v229, v228
	v_bfi_b32 v223, v188, v231, v230
	ds_bpermute_b32 v228, v185, v68
	ds_bpermute_b32 v229, v185, v64
	ds_bpermute_b32 v230, v185, v69
	ds_bpermute_b32 v231, v185, v65
	s_waitcnt lgkmcnt(0)
	v_bfi_b32 v224, v188, v229, v228
	v_bfi_b32 v225, v188, v231, v230
	ds_bpermute_b32 v228, v185, v70
	ds_bpermute_b32 v229, v185, v66
	ds_bpermute_b32 v230, v185, v71
	ds_bpermute_b32 v231, v185, v67
	s_waitcnt lgkmcnt(0)
	v_bfi_b32 v226, v188, v229, v228
	v_bfi_b32 v227, v188, v231, v230
	s_waitcnt vmcnt(4)
	v_pk_fma_f32 v[214:215], v[222:223], v[196:197], v[214:215]
	v_pk_fma_f32 v[212:213], v[220:221], v[194:195], v[212:213]
	v_pk_fma_f32 v[218:219], v[226:227], v[196:197], v[218:219]
	v_pk_fma_f32 v[216:217], v[224:225], v[194:195], v[216:217]
	global_store_dwordx4 v[180:181], v[212:215], off offset:512
	global_store_dwordx4 v[198:199], v[216:219], off offset:512
	global_load_dwordx4 v[212:215], v[174:175], off offset:512
	global_load_dwordx4 v[216:219], v[176:177], off offset:512
	ds_bpermute_b32 v228, v184, v60
	ds_bpermute_b32 v229, v184, v56
	ds_bpermute_b32 v230, v184, v61
	ds_bpermute_b32 v231, v184, v57
	s_waitcnt lgkmcnt(0)
	v_bfi_b32 v220, v188, v229, v228
	v_bfi_b32 v221, v188, v231, v230
	ds_bpermute_b32 v228, v184, v62
	ds_bpermute_b32 v229, v184, v58
	ds_bpermute_b32 v230, v184, v63
	ds_bpermute_b32 v231, v184, v59
	s_waitcnt lgkmcnt(0)
	v_bfi_b32 v222, v188, v229, v228
	v_bfi_b32 v223, v188, v231, v230
	ds_bpermute_b32 v228, v185, v60
	ds_bpermute_b32 v229, v185, v56
	ds_bpermute_b32 v230, v185, v61
	ds_bpermute_b32 v231, v185, v57
	s_waitcnt lgkmcnt(0)
	v_bfi_b32 v224, v188, v229, v228
	v_bfi_b32 v225, v188, v231, v230
	ds_bpermute_b32 v228, v185, v62
	ds_bpermute_b32 v229, v185, v58
	ds_bpermute_b32 v230, v185, v63
	ds_bpermute_b32 v231, v185, v59
	s_waitcnt lgkmcnt(0)
	v_bfi_b32 v226, v188, v229, v228
	v_bfi_b32 v227, v188, v231, v230
	s_waitcnt vmcnt(4)
	v_pk_fma_f32 v[206:207], v[222:223], v[192:193], v[206:207]
	v_pk_fma_f32 v[204:205], v[220:221], v[190:191], v[204:205]
	v_pk_fma_f32 v[210:211], v[226:227], v[192:193], v[210:211]
	v_pk_fma_f32 v[208:209], v[224:225], v[190:191], v[208:209]
	global_store_dwordx4 v[174:175], v[204:207], off
	global_store_dwordx4 v[176:177], v[208:211], off
	v_lshl_add_u64 v[178:179], v[168:169], 0, v[158:159]
	ds_bpermute_b32 v180, v184, v178
	ds_bpermute_b32 v181, v184, v179
	ds_bpermute_b32 v198, v185, v178
	ds_bpermute_b32 v199, v185, v179
	s_waitcnt lgkmcnt(0)
	v_lshl_add_u64 v[180:181], v[180:181], 0, v[186:187]
	v_lshl_add_u64 v[198:199], v[198:199], 0, v[186:187]
	global_load_dwordx4 v[204:207], v[180:181], off
	global_load_dwordx4 v[208:211], v[198:199], off
	ds_bpermute_b32 v228, v184, v52
	ds_bpermute_b32 v229, v184, v44
	ds_bpermute_b32 v230, v184, v53
	ds_bpermute_b32 v231, v184, v45
	s_waitcnt lgkmcnt(0)
	v_bfi_b32 v220, v188, v229, v228
	v_bfi_b32 v221, v188, v231, v230
	ds_bpermute_b32 v228, v184, v54
	ds_bpermute_b32 v229, v184, v46
	ds_bpermute_b32 v230, v184, v55
	ds_bpermute_b32 v231, v184, v47
	s_waitcnt lgkmcnt(0)
;     __device__ __forceinline__ void operator()(const pg8::f32x4 (&acc)[2][2][4][2], const pg8::Unit& u, int wr, int wc, int fr, int fq) const {
;     ...
;         for (int ai = 0; ai < 2; ++ai)
; #pragma unroll
;             for (int m = 0; m < 4; ++m) {
;                 float* rowp = base + (size_t)(ai * 128 + wr * 64 + m * 16 + fr) * DM + col0;
; #pragma unroll
;                 for (int bj = 0; bj < 2; ++bj)
; #pragma unroll
;                     for (int n = 0; n < 2; ++n) {
;                         pg8::f32x4* p = (pg8::f32x4*)(rowp + bj * 128 + n * 16);
;                         pg8::f32x4 xv = *p; xv = xv + gv[bj][n] * acc[ai][bj][m][n]; *p = xv;
;                     }
;                 if (m & 1) asm volatile("" ::: "memory");
	v_bfi_b32 v222, v188, v229, v228
	v_bfi_b32 v223, v188, v231, v230
	ds_bpermute_b32 v228, v185, v52
	ds_bpermute_b32 v229, v185, v44
	ds_bpermute_b32 v230, v185, v53
	ds_bpermute_b32 v231, v185, v45
	s_waitcnt lgkmcnt(0)
	v_bfi_b32 v224, v188, v229, v228
	v_bfi_b32 v225, v188, v231, v230
	ds_bpermute_b32 v228, v185, v54
	ds_bpermute_b32 v229, v185, v46
	ds_bpermute_b32 v230, v185, v55
	ds_bpermute_b32 v231, v185, v47
	s_waitcnt lgkmcnt(0)
	v_bfi_b32 v226, v188, v229, v228
	v_bfi_b32 v227, v188, v231, v230
	s_waitcnt vmcnt(4)
	v_pk_fma_f32 v[214:215], v[222:223], v[196:197], v[214:215]
	v_pk_fma_f32 v[212:213], v[220:221], v[194:195], v[212:213]
	v_pk_fma_f32 v[218:219], v[226:227], v[196:197], v[218:219]
	v_pk_fma_f32 v[216:217], v[224:225], v[194:195], v[216:217]
	global_store_dwordx4 v[174:175], v[212:215], off offset:512
	global_store_dwordx4 v[176:177], v[216:219], off offset:512
	global_load_dwordx4 v[212:215], v[180:181], off offset:512
	global_load_dwordx4 v[216:219], v[198:199], off offset:512
	ds_bpermute_b32 v228, v184, v48
	ds_bpermute_b32 v229, v184, v40
	ds_bpermute_b32 v230, v184, v49
	ds_bpermute_b32 v231, v184, v41
	s_waitcnt lgkmcnt(0)
	v_bfi_b32 v220, v188, v229, v228
	v_bfi_b32 v221, v188, v231, v230
	ds_bpermute_b32 v228, v184, v50
	ds_bpermute_b32 v229, v184, v42
	ds_bpermute_b32 v230, v184, v51
	ds_bpermute_b32 v231, v184, v43
	s_waitcnt lgkmcnt(0)
	v_bfi_b32 v222, v188, v229, v228
	v_bfi_b32 v223, v188, v231, v230
	ds_bpermute_b32 v228, v185, v48
	ds_bpermute_b32 v229, v185, v40
	ds_bpermute_b32 v230, v185, v49
	ds_bpermute_b32 v231, v185, v41
	s_waitcnt lgkmcnt(0)
	v_bfi_b32 v224, v188, v229, v228
	v_bfi_b32 v225, v188, v231, v230
	ds_bpermute_b32 v228, v185, v50
	ds_bpermute_b32 v229, v185, v42
	ds_bpermute_b32 v230, v185, v51
	ds_bpermute_b32 v231, v185, v43
	s_waitcnt lgkmcnt(0)
	v_bfi_b32 v226, v188, v229, v228
	v_bfi_b32 v227, v188, v231, v230
	s_waitcnt vmcnt(4)
	v_pk_fma_f32 v[206:207], v[222:223], v[192:193], v[206:207]
	v_pk_fma_f32 v[204:205], v[220:221], v[190:191], v[204:205]
	v_pk_fma_f32 v[210:211], v[226:227], v[192:193], v[210:211]
	v_pk_fma_f32 v[208:209], v[224:225], v[190:191], v[208:209]
	global_store_dwordx4 v[180:181], v[204:207], off
	global_store_dwordx4 v[198:199], v[208:211], off
	v_lshl_add_u64 v[178:179], v[168:169], 0, v[160:161]
	ds_bpermute_b32 v174, v184, v178
	ds_bpermute_b32 v175, v184, v179
	ds_bpermute_b32 v176, v185, v178
	ds_bpermute_b32 v177, v185, v179
	s_waitcnt lgkmcnt(0)
	v_lshl_add_u64 v[174:175], v[174:175], 0, v[186:187]
	v_lshl_add_u64 v[176:177], v[176:177], 0, v[186:187]
	global_load_dwordx4 v[204:207], v[174:175], off
	global_load_dwordx4 v[208:211], v[176:177], off
	ds_bpermute_b32 v228, v184, v36
	ds_bpermute_b32 v229, v184, v32
	ds_bpermute_b32 v230, v184, v37
	ds_bpermute_b32 v231, v184, v33
	s_waitcnt lgkmcnt(0)
	v_bfi_b32 v220, v188, v229, v228
	v_bfi_b32 v221, v188, v231, v230
	ds_bpermute_b32 v228, v184, v38
	ds_bpermute_b32 v229, v184, v34
	ds_bpermute_b32 v230, v184, v39
	ds_bpermute_b32 v231, v184, v35
	s_waitcnt lgkmcnt(0)
	v_bfi_b32 v222, v188, v229, v228
	v_bfi_b32 v223, v188, v231, v230
	ds_bpermute_b32 v228, v185, v36
	ds_bpermute_b32 v229, v185, v32
	ds_bpermute_b32 v230, v185, v37
	ds_bpermute_b32 v231, v185, v33
	s_waitcnt lgkmcnt(0)
	v_bfi_b32 v224, v188, v229, v228
	v_bfi_b32 v225, v188, v231, v230
	ds_bpermute_b32 v228, v185, v38
	ds_bpermute_b32 v229, v185, v34
	ds_bpermute_b32 v230, v185, v39
	ds_bpermute_b32 v231, v185, v35
	s_waitcnt lgkmcnt(0)
	v_bfi_b32 v226, v188, v229, v228
	v_bfi_b32 v227, v188, v231, v230
	s_waitcnt vmcnt(4)
	v_pk_fma_f32 v[214:215], v[222:223], v[196:197], v[214:215]
	v_pk_fma_f32 v[212:213], v[220:221], v[194:195], v[212:213]
	v_pk_fma_f32 v[218:219], v[226:227], v[196:197], v[218:219]
	v_pk_fma_f32 v[216:217], v[224:225], v[194:195], v[216:217]
	global_store_dwordx4 v[180:181], v[212:215], off offset:512
	global_store_dwordx4 v[198:199], v[216:219], off offset:512
	global_load_dwordx4 v[212:215], v[174:175], off offset:512
	global_load_dwordx4 v[216:219], v[176:177], off offset:512
	ds_bpermute_b32 v228, v184, v28
	ds_bpermute_b32 v229, v184, v24
	ds_bpermute_b32 v230, v184, v29
	ds_bpermute_b32 v231, v184, v25
	s_waitcnt lgkmcnt(0)
	v_bfi_b32 v220, v188, v229, v228
	v_bfi_b32 v221, v188, v231, v230
	ds_bpermute_b32 v228, v184, v30
	ds_bpermute_b32 v229, v184, v26
	ds_bpermute_b32 v230, v184, v31
	ds_bpermute_b32 v231, v184, v27
	s_waitcnt lgkmcnt(0)
	v_bfi_b32 v222, v188, v229, v228
	v_bfi_b32 v223, v188, v231, v230
	ds_bpermute_b32 v228, v185, v28
	ds_bpermute_b32 v229, v185, v24
	ds_bpermute_b32 v230, v185, v29
	ds_bpermute_b32 v231, v185, v25
	s_waitcnt lgkmcnt(0)
	v_bfi_b32 v224, v188, v229, v228
	v_bfi_b32 v225, v188, v231, v230
	ds_bpermute_b32 v228, v185, v30
	ds_bpermute_b32 v229, v185, v26
	ds_bpermute_b32 v230, v185, v31
	ds_bpermute_b32 v231, v185, v27
	s_waitcnt lgkmcnt(0)
;     __device__ __forceinline__ void operator()(const pg8::f32x4 (&acc)[2][2][4][2], const pg8::Unit& u, int wr, int wc, int fr, int fq) const {
;     ...
;         for (int ai = 0; ai < 2; ++ai)
; #pragma unroll
;             for (int m = 0; m < 4; ++m) {
;                 float* rowp = base + (size_t)(ai * 128 + wr * 64 + m * 16 + fr) * DM + col0;
; #pragma unroll
;                 for (int bj = 0; bj < 2; ++bj)
; #pragma unroll
;                     for (int n = 0; n < 2; ++n) {
;                         pg8::f32x4* p = (pg8::f32x4*)(rowp + bj * 128 + n * 16);
;                         pg8::f32x4 xv = *p; xv = xv + gv[bj][n] * acc[ai][bj][m][n]; *p = xv;
;                     }
;                 if (m & 1) asm volatile("" ::: "memory");
	v_bfi_b32 v226, v188, v229, v228
	v_bfi_b32 v227, v188, v231, v230
	s_waitcnt vmcnt(4)
	v_pk_fma_f32 v[206:207], v[222:223], v[192:193], v[206:207]
	v_pk_fma_f32 v[204:205], v[220:221], v[190:191], v[204:205]
	v_pk_fma_f32 v[210:211], v[226:227], v[192:193], v[210:211]
	v_pk_fma_f32 v[208:209], v[224:225], v[190:191], v[208:209]
	global_store_dwordx4 v[174:175], v[204:207], off
	global_store_dwordx4 v[176:177], v[208:211], off
	v_lshl_add_u64 v[178:179], v[168:169], 0, v[162:163]
	ds_bpermute_b32 v180, v184, v178
	ds_bpermute_b32 v181, v184, v179
	ds_bpermute_b32 v198, v185, v178
	ds_bpermute_b32 v199, v185, v179
	s_waitcnt lgkmcnt(0)
	v_lshl_add_u64 v[180:181], v[180:181], 0, v[186:187]
	v_lshl_add_u64 v[198:199], v[198:199], 0, v[186:187]
	global_load_dwordx4 v[204:207], v[180:181], off
	global_load_dwordx4 v[208:211], v[198:199], off
	ds_bpermute_b32 v228, v184, v20
	ds_bpermute_b32 v229, v184, v12
	ds_bpermute_b32 v230, v184, v21
	ds_bpermute_b32 v231, v184, v13
	s_waitcnt lgkmcnt(0)
	v_bfi_b32 v220, v188, v229, v228
	v_bfi_b32 v221, v188, v231, v230
	ds_bpermute_b32 v228, v184, v22
	ds_bpermute_b32 v229, v184, v14
	ds_bpermute_b32 v230, v184, v23
	ds_bpermute_b32 v231, v184, v15
	s_waitcnt lgkmcnt(0)
	v_bfi_b32 v222, v188, v229, v228
	v_bfi_b32 v223, v188, v231, v230
	ds_bpermute_b32 v228, v185, v20
	ds_bpermute_b32 v229, v185, v12
	ds_bpermute_b32 v230, v185, v21
	ds_bpermute_b32 v231, v185, v13
	s_waitcnt lgkmcnt(0)
	v_bfi_b32 v224, v188, v229, v228
	v_bfi_b32 v225, v188, v231, v230
	ds_bpermute_b32 v228, v185, v22
	ds_bpermute_b32 v229, v185, v14
	ds_bpermute_b32 v230, v185, v23
	ds_bpermute_b32 v231, v185, v15
	s_waitcnt lgkmcnt(0)
	v_bfi_b32 v226, v188, v229, v228
	v_bfi_b32 v227, v188, v231, v230
	s_waitcnt vmcnt(4)
	v_pk_fma_f32 v[214:215], v[222:223], v[196:197], v[214:215]
	v_pk_fma_f32 v[212:213], v[220:221], v[194:195], v[212:213]
	v_pk_fma_f32 v[218:219], v[226:227], v[196:197], v[218:219]
	v_pk_fma_f32 v[216:217], v[224:225], v[194:195], v[216:217]
	global_store_dwordx4 v[174:175], v[212:215], off offset:512
	global_store_dwordx4 v[176:177], v[216:219], off offset:512
	global_load_dwordx4 v[212:215], v[180:181], off offset:512
	global_load_dwordx4 v[216:219], v[198:199], off offset:512
	ds_bpermute_b32 v228, v184, v16
	ds_bpermute_b32 v229, v184, v8
	ds_bpermute_b32 v230, v184, v17
	ds_bpermute_b32 v231, v184, v9
	s_waitcnt lgkmcnt(0)
	v_bfi_b32 v220, v188, v229, v228
	v_bfi_b32 v221, v188, v231, v230
	ds_bpermute_b32 v228, v184, v18
	ds_bpermute_b32 v229, v184, v10
	ds_bpermute_b32 v230, v184, v19
	ds_bpermute_b32 v231, v184, v11
	s_waitcnt lgkmcnt(0)
	v_bfi_b32 v222, v188, v229, v228
	v_bfi_b32 v223, v188, v231, v230
	ds_bpermute_b32 v228, v185, v16
	ds_bpermute_b32 v229, v185, v8
	ds_bpermute_b32 v230, v185, v17
	ds_bpermute_b32 v231, v185, v9
	s_waitcnt lgkmcnt(0)
	v_bfi_b32 v224, v188, v229, v228
	v_bfi_b32 v225, v188, v231, v230
	ds_bpermute_b32 v228, v185, v18
	ds_bpermute_b32 v229, v185, v10
	ds_bpermute_b32 v230, v185, v19
	ds_bpermute_b32 v231, v185, v11
	s_waitcnt lgkmcnt(0)
	v_bfi_b32 v226, v188, v229, v228
	v_bfi_b32 v227, v188, v231, v230
	s_waitcnt vmcnt(4)
	v_pk_fma_f32 v[206:207], v[222:223], v[192:193], v[206:207]
	v_pk_fma_f32 v[204:205], v[220:221], v[190:191], v[204:205]
	v_pk_fma_f32 v[210:211], v[226:227], v[192:193], v[210:211]
	v_pk_fma_f32 v[208:209], v[224:225], v[190:191], v[208:209]
	global_store_dwordx4 v[180:181], v[204:207], off
	global_store_dwordx4 v[198:199], v[208:211], off
	ds_bpermute_b32 v228, v184, v4
	ds_bpermute_b32 v229, v184, v0
	ds_bpermute_b32 v230, v184, v5
	ds_bpermute_b32 v231, v184, v1
	s_waitcnt lgkmcnt(0)
	v_bfi_b32 v220, v188, v229, v228
	v_bfi_b32 v221, v188, v231, v230
	ds_bpermute_b32 v228, v184, v6
	ds_bpermute_b32 v229, v184, v2
	ds_bpermute_b32 v230, v184, v7
	ds_bpermute_b32 v231, v184, v3
	s_waitcnt lgkmcnt(0)
	v_bfi_b32 v222, v188, v229, v228
	v_bfi_b32 v223, v188, v231, v230
	ds_bpermute_b32 v228, v185, v4
	ds_bpermute_b32 v229, v185, v0
	ds_bpermute_b32 v230, v185, v5
	ds_bpermute_b32 v231, v185, v1
	s_waitcnt lgkmcnt(0)
	v_bfi_b32 v224, v188, v229, v228
	v_bfi_b32 v225, v188, v231, v230
	ds_bpermute_b32 v228, v185, v6
	ds_bpermute_b32 v229, v185, v2
	ds_bpermute_b32 v230, v185, v7
	ds_bpermute_b32 v231, v185, v3
	s_waitcnt lgkmcnt(0)
	v_bfi_b32 v226, v188, v229, v228
	v_bfi_b32 v227, v188, v231, v230
	s_waitcnt vmcnt(2)
	v_pk_fma_f32 v[214:215], v[222:223], v[196:197], v[214:215]
	v_pk_fma_f32 v[212:213], v[220:221], v[194:195], v[212:213]
	v_pk_fma_f32 v[218:219], v[226:227], v[196:197], v[218:219]
	v_pk_fma_f32 v[216:217], v[224:225], v[194:195], v[216:217]
	global_store_dwordx4 v[180:181], v[212:215], off offset:512
	global_store_dwordx4 v[198:199], v[216:219], off offset:512
	s_cbranch_vccnz .LBB0_1111
	s_andn2_b64 vcc, exec, s[0:1]
	s_cbranch_vccnz .LBB0_1110
	s_barrier
	s_branch .LBB0_1110
